# RWKV: epilogue waves no longer drain their stores per block (skip wait ladder), their prefetch moved after first Y tile, per-channel parameter loads hoisted out of the block loop; GEMM loops: dead sec
# baseline (speedup 1.0000x reference)
.LBB0_100:
	v_mov_b32_e32 v129, 0
	s_andn2_b64 vcc, exec, s[40:41]
	v_mov_b32_e32 v128, v129
	v_mov_b32_e32 v127, v129
	v_mov_b32_e32 v126, v129
	v_mov_b32_e32 v125, v129
	v_mov_b32_e32 v124, v129
	v_mov_b32_e32 v123, v129
	v_mov_b32_e32 v122, v129
	v_mov_b32_e32 v121, v129
	v_mov_b32_e32 v120, v129
	v_mov_b32_e32 v119, v129
	v_mov_b32_e32 v118, v129
	v_mov_b32_e32 v117, v129
	v_mov_b32_e32 v116, v129
	v_mov_b32_e32 v115, v129
	v_mov_b32_e32 v114, v129
	v_mov_b32_e32 v97, v129
	v_mov_b32_e32 v96, v129
	v_mov_b32_e32 v95, v129
	v_mov_b32_e32 v94, v129
	v_mov_b32_e32 v93, v129
	v_mov_b32_e32 v92, v129
	v_mov_b32_e32 v91, v129
	v_mov_b32_e32 v90, v129
	v_mov_b32_e32 v89, v129
	v_mov_b32_e32 v88, v129
	v_mov_b32_e32 v87, v129
	v_mov_b32_e32 v86, v129
	v_mov_b32_e32 v85, v129
	v_mov_b32_e32 v84, v129
	v_mov_b32_e32 v83, v129
	v_mov_b32_e32 v82, v129
	v_mov_b32_e32 v113, v129
	v_mov_b32_e32 v112, v129
	v_mov_b32_e32 v111, v129
	v_mov_b32_e32 v110, v129
	v_mov_b32_e32 v109, v129
	v_mov_b32_e32 v108, v129
	v_mov_b32_e32 v107, v129
	v_mov_b32_e32 v106, v129
	v_mov_b32_e32 v105, v129
	v_mov_b32_e32 v104, v129
	v_mov_b32_e32 v103, v129
	v_mov_b32_e32 v102, v129
	v_mov_b32_e32 v101, v129
	v_mov_b32_e32 v100, v129
	v_mov_b32_e32 v99, v129
	v_mov_b32_e32 v98, v129
	v_mov_b32_e32 v81, v129
	v_mov_b32_e32 v80, v129
	v_mov_b32_e32 v79, v129
	v_mov_b32_e32 v78, v129
	v_mov_b32_e32 v77, v129
	v_mov_b32_e32 v76, v129
	v_mov_b32_e32 v75, v129
	v_mov_b32_e32 v74, v129
	v_mov_b32_e32 v73, v129
	v_mov_b32_e32 v72, v129
	v_mov_b32_e32 v71, v129
	v_mov_b32_e32 v70, v129
	v_mov_b32_e32 v69, v129
	v_mov_b32_e32 v68, v129
	v_mov_b32_e32 v67, v129
	v_mov_b32_e32 v66, v129
	v_mov_b32_e32 v65, v129
	v_mov_b32_e32 v64, v129
	v_mov_b32_e32 v63, v129
	v_mov_b32_e32 v62, v129
	v_mov_b32_e32 v61, v129
	v_mov_b32_e32 v60, v129
	v_mov_b32_e32 v59, v129
	v_mov_b32_e32 v58, v129
	v_mov_b32_e32 v57, v129
	v_mov_b32_e32 v56, v129
	v_mov_b32_e32 v55, v129
	v_mov_b32_e32 v54, v129
	v_mov_b32_e32 v53, v129
	v_mov_b32_e32 v52, v129
	v_mov_b32_e32 v51, v129
	v_mov_b32_e32 v50, v129
	v_mov_b32_e32 v33, v129
	v_mov_b32_e32 v32, v129
	v_mov_b32_e32 v31, v129
	v_mov_b32_e32 v30, v129
	v_mov_b32_e32 v29, v129
	v_mov_b32_e32 v28, v129
	v_mov_b32_e32 v27, v129
	v_mov_b32_e32 v26, v129
	v_mov_b32_e32 v25, v129
	v_mov_b32_e32 v24, v129
	v_mov_b32_e32 v23, v129
	v_mov_b32_e32 v22, v129
	v_mov_b32_e32 v21, v129
	v_mov_b32_e32 v20, v129
	v_mov_b32_e32 v19, v129
	v_mov_b32_e32 v18, v129
	v_mov_b32_e32 v49, v129
	v_mov_b32_e32 v48, v129
	v_mov_b32_e32 v47, v129
	v_mov_b32_e32 v46, v129
	v_mov_b32_e32 v45, v129
	v_mov_b32_e32 v44, v129
	v_mov_b32_e32 v43, v129
	v_mov_b32_e32 v42, v129
	v_mov_b32_e32 v41, v129
	v_mov_b32_e32 v40, v129
	v_mov_b32_e32 v39, v129
	v_mov_b32_e32 v38, v129
	v_mov_b32_e32 v37, v129
	v_mov_b32_e32 v36, v129
	v_mov_b32_e32 v35, v129
	v_mov_b32_e32 v34, v129
	v_mov_b32_e32 v17, v129
	v_mov_b32_e32 v16, v129
	v_mov_b32_e32 v15, v129
	v_mov_b32_e32 v14, v129
	v_mov_b32_e32 v13, v129
	v_mov_b32_e32 v12, v129
	v_mov_b32_e32 v11, v129
	v_mov_b32_e32 v10, v129
	v_mov_b32_e32 v9, v129
	v_mov_b32_e32 v8, v129
	v_mov_b32_e32 v7, v129
	v_mov_b32_e32 v6, v129
	v_mov_b32_e32 v5, v129
	v_mov_b32_e32 v4, v129
	v_mov_b32_e32 v3, v129
	v_mov_b32_e32 v2, v129
	s_cbranch_vccnz .LBB0_103
	s_add_u32 s78, s78, 0x80
	s_addc_u32 s79, s79, 0
	s_add_u32 s73, s80, 0x100
	s_addc_u32 vcc_lo, s81, 0
	s_mov_b32 s80, 0

.LBB0_468:
	v_mov_b32_e32 v129, 0
	s_andn2_b64 vcc, exec, s[46:47]
	v_mov_b32_e32 v128, v129
	v_mov_b32_e32 v127, v129
	v_mov_b32_e32 v126, v129
	v_mov_b32_e32 v125, v129
	v_mov_b32_e32 v124, v129
	v_mov_b32_e32 v123, v129
	v_mov_b32_e32 v122, v129
	v_mov_b32_e32 v113, v129
	v_mov_b32_e32 v112, v129
	v_mov_b32_e32 v111, v129
	v_mov_b32_e32 v110, v129
	v_mov_b32_e32 v109, v129
	v_mov_b32_e32 v108, v129
	v_mov_b32_e32 v107, v129
	v_mov_b32_e32 v106, v129
	v_mov_b32_e32 v97, v129
	v_mov_b32_e32 v96, v129
	v_mov_b32_e32 v95, v129
	v_mov_b32_e32 v94, v129
	v_mov_b32_e32 v93, v129
	v_mov_b32_e32 v92, v129
	v_mov_b32_e32 v91, v129
	v_mov_b32_e32 v90, v129
	v_mov_b32_e32 v81, v129
	v_mov_b32_e32 v80, v129
	v_mov_b32_e32 v79, v129
	v_mov_b32_e32 v78, v129
	v_mov_b32_e32 v77, v129
	v_mov_b32_e32 v76, v129
	v_mov_b32_e32 v75, v129
	v_mov_b32_e32 v74, v129
	v_mov_b32_e32 v121, v129
	v_mov_b32_e32 v120, v129
	v_mov_b32_e32 v119, v129
	v_mov_b32_e32 v118, v129
	v_mov_b32_e32 v117, v129
	v_mov_b32_e32 v116, v129
	v_mov_b32_e32 v115, v129
	v_mov_b32_e32 v114, v129
	v_mov_b32_e32 v105, v129
	v_mov_b32_e32 v104, v129
	v_mov_b32_e32 v103, v129
	v_mov_b32_e32 v102, v129
	v_mov_b32_e32 v101, v129
	v_mov_b32_e32 v100, v129
	v_mov_b32_e32 v99, v129
	v_mov_b32_e32 v98, v129
	v_mov_b32_e32 v89, v129
	v_mov_b32_e32 v88, v129
	v_mov_b32_e32 v87, v129
	v_mov_b32_e32 v86, v129
	v_mov_b32_e32 v85, v129
	v_mov_b32_e32 v84, v129
	v_mov_b32_e32 v83, v129
	v_mov_b32_e32 v82, v129
	v_mov_b32_e32 v73, v129
	v_mov_b32_e32 v72, v129
	v_mov_b32_e32 v71, v129
	v_mov_b32_e32 v70, v129
	v_mov_b32_e32 v69, v129
	v_mov_b32_e32 v68, v129
	v_mov_b32_e32 v67, v129
	v_mov_b32_e32 v66, v129
	v_mov_b32_e32 v65, v129
	v_mov_b32_e32 v64, v129
	v_mov_b32_e32 v63, v129
	v_mov_b32_e32 v62, v129
	v_mov_b32_e32 v61, v129
	v_mov_b32_e32 v60, v129
	v_mov_b32_e32 v59, v129
	v_mov_b32_e32 v58, v129
	v_mov_b32_e32 v49, v129
	v_mov_b32_e32 v48, v129
	v_mov_b32_e32 v47, v129
	v_mov_b32_e32 v46, v129
	v_mov_b32_e32 v45, v129
	v_mov_b32_e32 v44, v129
	v_mov_b32_e32 v43, v129
	v_mov_b32_e32 v42, v129
	v_mov_b32_e32 v33, v129
	v_mov_b32_e32 v32, v129
	v_mov_b32_e32 v31, v129
	v_mov_b32_e32 v30, v129
	v_mov_b32_e32 v29, v129
	v_mov_b32_e32 v28, v129
	v_mov_b32_e32 v27, v129
	v_mov_b32_e32 v26, v129
	v_mov_b32_e32 v17, v129
	v_mov_b32_e32 v16, v129
	v_mov_b32_e32 v15, v129
	v_mov_b32_e32 v14, v129
	v_mov_b32_e32 v13, v129
	v_mov_b32_e32 v12, v129
	v_mov_b32_e32 v11, v129
	v_mov_b32_e32 v10, v129
	v_mov_b32_e32 v57, v129
	v_mov_b32_e32 v56, v129
	v_mov_b32_e32 v55, v129
	v_mov_b32_e32 v54, v129
	v_mov_b32_e32 v53, v129
	v_mov_b32_e32 v52, v129
	v_mov_b32_e32 v51, v129
	v_mov_b32_e32 v50, v129
	v_mov_b32_e32 v41, v129
	v_mov_b32_e32 v40, v129
	v_mov_b32_e32 v39, v129
	v_mov_b32_e32 v38, v129
	v_mov_b32_e32 v37, v129
	v_mov_b32_e32 v36, v129
	v_mov_b32_e32 v35, v129
	v_mov_b32_e32 v34, v129
	v_mov_b32_e32 v25, v129
	v_mov_b32_e32 v24, v129
	v_mov_b32_e32 v23, v129
	v_mov_b32_e32 v22, v129
	v_mov_b32_e32 v21, v129
	v_mov_b32_e32 v20, v129
	v_mov_b32_e32 v19, v129
	v_mov_b32_e32 v18, v129
	v_mov_b32_e32 v9, v129
	v_mov_b32_e32 v8, v129
	v_mov_b32_e32 v7, v129
	v_mov_b32_e32 v6, v129
	v_mov_b32_e32 v5, v129
	v_mov_b32_e32 v4, v129
	v_mov_b32_e32 v3, v129
	v_mov_b32_e32 v2, v129
	s_cbranch_vccnz .LBB0_471
	s_add_u32 s50, s50, 0x80
	s_addc_u32 s51, s51, 0
	s_add_u32 s88, s62, 0x100
	s_addc_u32 s89, s63, 0
	s_mov_b32 s62, 0

.LBB0_560:
	s_and_b64 vcc, exec, s[0:1]
	s_cbranch_vccz .LBB0_532
	v_mov_b32_e32 v1, v180
	s_ashr_i32 s0, s71, 3
	v_ashrrev_i32_e32 v75, 6, v1
	v_and_b32_e32 v77, 63, v1
	v_lshlrev_b32_e32 v1, 10, v75
	s_waitcnt vmcnt(6)
	v_lshlrev_b32_e32 v2, 2, v77
	v_add3_u32 v1, s90, v1, v2
	s_ashr_i32 s1, s0, 31
	v_lshlrev_b32_e32 v2, 3, v75
	s_lshl_b64 s[80:81], s[0:1], 11
	v_ashrrev_i32_e32 v3, 31, v2
	v_lshl_add_u64 v[2:3], s[80:81], 0, v[2:3]
	s_lshl_b32 s0, s71, 6
	s_and_b32 s72, s0, 0x1c0
	v_add_u32_e32 v100, s72, v77
	v_mov_b32_e32 v101, 0
	v_lshlrev_b64 v[100:101], 2, v[100:101]
	v_lshl_add_u64 v[102:103], s[42:43], 0, v[100:101]
	global_load_dword v115, v[102:103], off
	global_load_dword v116, v[102:103], off offset:2048
	s_add_u32 s0, s42, s88
	s_addc_u32 s1, s43, 0
	v_lshl_add_u64 v[104:105], s[48:49], 0, v[100:101]
	global_load_dword v117, v[104:105], off
	v_lshl_add_u64 v[104:105], s[44:45], 0, v[100:101]
	global_load_dword v118, v[104:105], off
	v_lshl_add_u64 v[104:105], s[0:1], 0, v[100:101]
	global_load_dword v119, v[104:105], off
	v_lshl_add_u64 v[104:105], s[52:53], 0, v[100:101]
	global_load_dword v120, v[104:105], off
	v_lshl_add_u64 v[104:105], s[54:55], 0, v[100:101]
	global_load_dword v121, v[104:105], off
	v_lshl_add_u64 v[104:105], s[56:57], 0, v[100:101]
	global_load_dword v122, v[104:105], off
	v_mad_u64_u32 v[4:5], s[0:1], v2, s83, 0
	ds_write2st64_b32 v1, v94, v94 offset1:1
	ds_write2st64_b32 v1, v94, v94 offset0:2 offset1:3
	v_or_b32_e32 v1, s72, v77
	v_mad_i32_i24 v5, v3, s83, v5
	v_mov_b32_e32 v95, v94
	v_cmp_lt_i32_e32 vcc, 0, v75
	s_mov_b32 s40, 0
	v_mov_b32_e32 v106, 0
	v_lshl_add_u64 v[4:5], s[46:47], 0, v[4:5]
	s_waitcnt vmcnt(5)
	v_lshlrev_b32_e32 v6, 1, v1
	v_mov_b64_e32 v[34:35], v[94:95]
	s_and_saveexec_b64 s[0:1], vcc
	s_cbranch_execz .LBB0_563
	v_mov_b32_e32 v7, v94
	v_lshl_add_u64 v[8:9], v[4:5], 0, v[6:7]
	global_load_ushort v7, v[8:9], off offset:-3072
	global_load_ushort v10, v[8:9], off offset:-2048
	s_nop 0
	global_load_ushort v8, v[8:9], off offset:-1024
	s_waitcnt vmcnt(2)
	v_lshlrev_b32_e32 v106, 16, v7
	s_waitcnt vmcnt(1)
	v_lshlrev_b32_e32 v35, 16, v10
	s_waitcnt vmcnt(0)
	v_lshlrev_b32_e32 v34, 16, v8
.LBB0_563:
	s_or_b64 exec, exec, s[0:1]
	v_lshlrev_b64 v[2:3], 9, v[2:3]
	v_mov_b32_e32 v7, v94
	v_or_b32_e32 v2, v2, v1
	v_lshl_add_u64 v[4:5], v[4:5], 0, v[6:7]
	v_lshl_add_u64 v[8:9], v[2:3], 2, s[34:35]
	v_lshl_add_u64 v[6:7], v[2:3], 1, s[62:63]
	s_waitcnt vmcnt(4)
	v_lshl_add_u64 v[10:11], v[4:5], 0, s[76:77]
	global_load_dword v107, v[8:9], off
	global_load_ushort v18, v[4:5], off
	global_load_ushort v1, v[4:5], off offset:3072
	global_load_ushort v19, v[10:11], off offset:1024
	global_load_ushort v20, v[4:5], off offset:1024
	global_load_ushort v21, v[10:11], off offset:2048
	global_load_ushort v22, v[6:7], off
	global_load_ushort v23, v[4:5], off offset:2048
	v_or_b32_e32 v4, 0x200, v2
	v_mov_b32_e32 v5, v3
	v_lshl_add_u64 v[6:7], v[4:5], 1, s[62:63]
	v_lshl_add_u64 v[4:5], v[4:5], 2, s[34:35]
	v_or_b32_e32 v12, 0x400, v2
	v_mov_b32_e32 v13, v3
	v_lshl_add_u64 v[8:9], v[10:11], 0, s[76:77]
	s_waitcnt vmcnt(11)
	v_lshl_add_u64 v[14:15], v[12:13], 1, s[62:63]
	v_lshl_add_u64 v[12:13], v[12:13], 2, s[34:35]
	global_load_ushort v24, v[6:7], off
	global_load_dword v108, v[4:5], off
	global_load_ushort v25, v[8:9], off offset:3072
	global_load_ushort v26, v[8:9], off offset:1024
	global_load_ushort v27, v[14:15], off
	global_load_dword v109, v[12:13], off
	global_load_ushort v28, v[8:9], off offset:2048
	global_load_ushort v29, v[10:11], off offset:3072
	v_or_b32_e32 v4, 0x600, v2
	v_mov_b32_e32 v5, v3
	v_lshl_add_u64 v[16:17], v[8:9], 0, s[76:77]
	v_lshl_add_u64 v[6:7], v[4:5], 1, s[62:63]
	v_lshl_add_u64 v[4:5], v[4:5], 2, s[34:35]
	v_lshl_add_u64 v[8:9], v[16:17], 0, s[76:77]
	global_load_ushort v30, v[16:17], off offset:1024
	global_load_ushort v31, v[16:17], off offset:2048
	global_load_ushort v32, v[6:7], off
	global_load_dword v110, v[4:5], off
	global_load_ushort v33, v[8:9], off offset:3072
	global_load_ushort v36, v[8:9], off offset:1024
	global_load_ushort v37, v[8:9], off offset:2048
	s_nop 0
	global_load_ushort v16, v[16:17], off offset:3072
	v_or_b32_e32 v4, 0xa00, v2
	v_mov_b32_e32 v5, v3
	v_or_b32_e32 v10, 0x800, v2
	v_mov_b32_e32 v11, v3
	v_lshl_add_u64 v[14:15], v[8:9], 0, s[76:77]
	v_lshl_add_u64 v[6:7], v[4:5], 1, s[62:63]
	v_lshl_add_u64 v[4:5], v[4:5], 2, s[34:35]
	v_lshl_add_u64 v[12:13], v[10:11], 1, s[62:63]
	global_load_ushort v17, v[14:15], off offset:1024
	global_load_ushort v38, v[14:15], off offset:2048
	global_load_ushort v39, v[6:7], off
	global_load_dword v112, v[4:5], off
	global_load_ushort v40, v[14:15], off offset:3072
	global_load_ushort v41, v[12:13], off
	v_lshl_add_u64 v[4:5], v[14:15], 0, s[76:77]
	v_or_b32_e32 v6, 0xc00, v2
	v_mov_b32_e32 v7, v3
	v_lshl_add_u64 v[12:13], v[4:5], 0, s[76:77]
	v_or_b32_e32 v2, 0xe00, v2
	v_lshl_add_u64 v[8:9], v[6:7], 1, s[62:63]
	global_load_ushort v14, v[12:13], off offset:1024
	s_nop 0
	global_load_ushort v12, v[12:13], off offset:2048
	s_nop 0
	global_load_ushort v13, v[4:5], off offset:3072
	global_load_ushort v15, v[4:5], off offset:1024
	global_load_ushort v42, v[4:5], off offset:2048
	v_lshl_add_u64 v[4:5], v[2:3], 1, s[62:63]
	global_load_ushort v43, v[4:5], off
	s_nop 0
	global_load_ushort v8, v[8:9], off
	v_lshl_add_u64 v[4:5], v[6:7], 2, s[34:35]
	v_lshl_add_u64 v[2:3], v[2:3], 2, s[34:35]
	v_lshl_add_u64 v[10:11], v[10:11], 2, s[34:35]
	global_load_dword v113, v[4:5], off
	global_load_dword v114, v[2:3], off
	global_load_dword v111, v[10:11], off
	s_waitcnt vmcnt(38)
	v_lshlrev_b32_e32 v44, 16, v18
	s_waitcnt vmcnt(37)
	v_lshlrev_b32_e32 v1, 16, v1
	s_waitcnt vmcnt(36)
	v_lshlrev_b32_e32 v45, 16, v19
	s_waitcnt vmcnt(35)
	v_lshlrev_b32_e32 v46, 16, v20
	s_waitcnt vmcnt(34)
	v_lshlrev_b32_e32 v47, 16, v21
	s_waitcnt vmcnt(33)
	v_lshlrev_b32_e32 v50, 16, v22
	s_waitcnt vmcnt(32)
	v_lshlrev_b32_e32 v48, 16, v23
	s_waitcnt vmcnt(31)
	v_lshlrev_b32_e32 v51, 16, v24
	s_waitcnt vmcnt(29)
	v_lshlrev_b32_e32 v49, 16, v25
	s_waitcnt vmcnt(28)
	v_lshlrev_b32_e32 v54, 16, v26
	s_waitcnt vmcnt(27)
	v_lshlrev_b32_e32 v58, 16, v27
	s_waitcnt vmcnt(25)
	v_lshlrev_b32_e32 v56, 16, v28
	s_waitcnt vmcnt(24)
	v_lshlrev_b32_e32 v52, 16, v29
	s_waitcnt vmcnt(23)
	v_lshlrev_b32_e32 v53, 16, v30
	s_waitcnt vmcnt(22)
	v_lshlrev_b32_e32 v55, 16, v31
	s_waitcnt vmcnt(21)
	v_lshlrev_b32_e32 v57, 16, v32
	s_waitcnt vmcnt(19)
	v_lshlrev_b32_e32 v59, 16, v33
	s_waitcnt vmcnt(18)
	v_lshlrev_b32_e32 v62, 16, v36
	s_waitcnt vmcnt(17)
	v_lshlrev_b32_e32 v64, 16, v37
	s_waitcnt vmcnt(16)
	v_lshlrev_b32_e32 v60, 16, v16
	v_mov_b64_e32 v[36:37], v[94:95]
	s_waitcnt vmcnt(15)
	v_lshlrev_b32_e32 v61, 16, v17
	s_waitcnt vmcnt(14)
	v_lshlrev_b32_e32 v63, 16, v38
	s_waitcnt vmcnt(13)
	v_lshlrev_b32_e32 v65, 16, v39
	v_mov_b64_e32 v[38:39], v[94:95]
	s_waitcnt vmcnt(11)
	v_lshlrev_b32_e32 v67, 16, v40
	s_waitcnt vmcnt(10)
	v_lshlrev_b32_e32 v66, 16, v41
	v_mov_b64_e32 v[40:41], v[94:95]
	s_waitcnt vmcnt(9)
	v_lshlrev_b32_e32 v70, 16, v14
	s_waitcnt vmcnt(8)
	v_lshlrev_b32_e32 v72, 16, v12
	s_waitcnt vmcnt(7)
	v_lshlrev_b32_e32 v68, 16, v13
	s_waitcnt vmcnt(6)
	v_lshlrev_b32_e32 v69, 16, v15
	s_waitcnt vmcnt(5)
	v_lshlrev_b32_e32 v71, 16, v42
	s_waitcnt vmcnt(4)
	v_lshlrev_b32_e32 v73, 16, v43
	s_waitcnt vmcnt(3)
	v_lshlrev_b32_e32 v74, 16, v8
	v_mov_b64_e32 v[42:43], v[94:95]
	v_mov_b32_e32 v224, 0
	v_mov_b32_e32 v225, 0
	v_mov_b32_e32 v226, 0
	v_mov_b32_e32 v227, 0
	v_mov_b32_e32 v228, 0
	v_mov_b32_e32 v229, 0
	v_mov_b32_e32 v230, 0
	v_mov_b32_e32 v231, 0
	v_mov_b32_e32 v232, 0
	v_mov_b32_e32 v233, 0
	v_mov_b32_e32 v234, 0
	v_mov_b32_e32 v235, 0
	v_mov_b32_e32 v236, 0
	v_mov_b32_e32 v237, 0
	v_mov_b32_e32 v238, 0
	v_mov_b32_e32 v239, 0
	v_mov_b32_e32 v179, 0x27f00
	ds_write_b32 v179, v224 offset:0
	ds_write_b32 v179, v224 offset:4
	ds_write_b32 v179, v224 offset:8
	ds_write_b32 v179, v224 offset:12
	ds_write_b32 v179, v224 offset:16
	ds_write_b32 v179, v224 offset:20
	ds_write_b32 v179, v224 offset:24
	ds_write_b32 v179, v224 offset:28
	s_waitcnt vmcnt(0)
.LBB0_564:
	v_mov_b32_e32 v78, v75
	v_mov_b32_e32 v76, v77
	s_and_b32 s3, s40, 1
	v_add_u32_e32 v28, s72, v76
	v_ashrrev_i32_e32 v29, 31, v28
	v_lshlrev_b64 v[10:11], 2, v[28:29]
	v_mov_b32_e32 v5, v115
	v_mov_b32_e32 v4, v116
	v_mov_b32_e32 v9, v117
	v_mov_b32_e32 v8, v118
	v_mov_b32_e32 v7, v119
	v_mov_b32_e32 v6, v120
	v_mov_b32_e32 v3, v121
	v_mov_b32_e32 v2, v122
	s_mov_b64 s[0:1], src_shared_base
	s_cmp_lg_u32 0, -1
	v_sub_f32_e32 v14, v35, v46
	s_cselect_b32 s4, s1, 0
	s_cselect_b32 s5, 0, 0
	v_mad_u64_u32 v[10:11], s[0:1], v78, s87, v[76:77]
	s_add_u32 s0, s5, 0x11800
	v_lshl_add_u32 v16, v10, 2, 0
	s_addc_u32 s1, s4, 0
	s_cmp_lg_u64 s[0:1], 0
	s_cselect_b32 s6, s0, -1
	s_add_i32 s7, 0, 0x17800
	s_add_u32 s0, s5, 0x23800
	s_addc_u32 s1, s4, 0
	s_cmp_lg_u64 s[0:1], 0
	s_cselect_b32 s0, s0, -1
	s_add_i32 s1, 0, 0x1b800
	s_cmp_eq_u32 s3, 0
	s_cselect_b32 s16, s0, s1
	v_sub_f32_e32 v13, v106, v44
	s_cselect_b32 s41, s6, s7
	v_sub_f32_e32 v15, v34, v48
	v_lshl_add_u32 v12, v76, 2, s41
	v_lshlrev_b32_e32 v26, 3, v78
	v_cmp_eq_u32_e32 vcc, 0, v76
	v_fma_f32 v13, v13, v5, v44
	v_fma_f32 v14, v14, v4, v46
	v_add_f32_e32 v10, v50, v9
	v_add_f32_e32 v11, v107, v8
	v_mul_f32_e32 v10, 0xbfb8aa3b, v10
	v_mul_f32_e32 v11, 0xbfb8aa3b, v11
	v_mul_f32_e32 v17, v14, v6
	v_exp_f32_e32 v10, v10
	v_exp_f32_e32 v11, v11
	v_mul_f32_e32 v18, v17, v17
	v_fma_f32 v15, v15, v7, v48
	v_add_f32_e32 v10, 1.0, v10
	v_mov_b32_dpp v18, v18 quad_perm:[1,0,3,2] row_mask:0xf bank_mask:0xf bound_ctrl:1
	v_fmac_f32_e32 v18, v17, v17
	v_add_f32_e32 v11, 1.0, v11
	v_rcp_f32_e32 v19, v10
	v_add_f32_dpp v18, v18, v18 quad_perm:[2,3,0,1] row_mask:0xf bank_mask:0xf bound_ctrl:1
	v_rcp_f32_e32 v20, v11
	s_nop 0
	v_add_f32_dpp v18, v18, v18 row_half_mirror row_mask:0xf bank_mask:0xf bound_ctrl:1
	s_nop 1
	v_add_f32_dpp v10, v18, v18 row_mirror row_mask:0xf bank_mask:0xf bound_ctrl:1
	v_mul_f32_e32 v18, 0xbf1b4598, v20
	v_readlane_b32 s3, v10, 16
	v_readlane_b32 s4, v10, 48
	v_readlane_b32 s0, v10, 0
	v_readlane_b32 s1, v10, 32
	v_mov_b32_e32 v10, s3
	v_mov_b32_e32 v11, s4
	v_pk_add_f32 v[10:11], s[0:1], v[10:11]
	v_mul_f32_e32 v18, 0x3fb8aa3b, v18
	v_add_f32_e32 v10, v10, v11
	v_add_f32_e32 v11, -1.0, v19
	v_add_f32_e32 v10, 0x2b8cbccc, v10
	v_fma_f32 v20, v3, v11, 1.0
	v_exp_f32_e32 v11, v18
	v_mul_f32_e32 v18, 0x4b800000, v10
	v_cmp_gt_f32_e64 s[0:1], s91, v10
	v_mul_f32_e32 v14, v14, v20
	s_nop 0
	v_cndmask_b32_e64 v10, v10, v18, s[0:1]
	v_rsq_f32_e32 v10, v10
	v_mul_f32_e32 v18, v13, v14
	v_mul_f32_e32 v20, v2, v18
	v_mul_f32_e32 v13, v13, v11
	v_mul_f32_e32 v21, 0x45800000, v10
	v_mov_b32_dpp v20, v20 quad_perm:[1,0,3,2] row_mask:0xf bank_mask:0xf bound_ctrl:1
	v_fmac_f32_e32 v20, v2, v18
	v_rcp_f32_e32 v18, v11
	v_cndmask_b32_e64 v10, v10, v21, s[0:1]
	v_mul_f32_e64 v10, v17, -v10
	v_add_f32_dpp v20, v20, v20 quad_perm:[2,3,0,1] row_mask:0xf bank_mask:0xf bound_ctrl:1
	ds_write2st64_b32 v16, v10, v13 offset1:68
	v_mul_f32_e64 v10, v19, -v10
	v_add_f32_dpp v20, v20, v20 row_half_mirror row_mask:0xf bank_mask:0xf bound_ctrl:1
	v_mul_f32_e32 v14, v18, v14
	v_mul_f32_e32 v10, v18, v10
	v_add_f32_dpp v20, v20, v20 row_mirror row_mask:0xf bank_mask:0xf bound_ctrl:1
	ds_write2st64_b32 v16, v10, v14 offset0:136 offset1:204
	v_lshl_add_u32 v10, v78, 11, v12
	v_readlane_b32 s0, v20, 0
	v_readlane_b32 s3, v20, 16
	v_readlane_b32 s1, v20, 32
	v_readlane_b32 s6, v20, 48
	ds_write_b32 v10, v15
	v_lshl_add_u32 v10, v26, 2, s16
	s_and_saveexec_b64 s[4:5], vcc
	v_mov_b32_e32 v14, s3
	v_mov_b32_e32 v15, s6
	v_pk_add_f32 v[14:15], s[0:1], v[14:15]
	s_nop 0
	v_add_f32_e32 v13, v14, v15
	ds_write_b32 v10, v13
	s_or_b64 exec, exec, s[4:5]
	v_add_f32_e32 v15, v51, v9
	v_mul_f32_e32 v15, 0xbfb8aa3b, v15
	v_add_f32_e32 v18, v108, v8
	v_exp_f32_e32 v15, v15
	v_mul_f32_e32 v18, 0xbfb8aa3b, v18
	v_exp_f32_e32 v18, v18
	v_sub_f32_e32 v13, v44, v1
	v_fma_f32 v17, v13, v5, v1
	v_sub_f32_e32 v13, v46, v45
	v_sub_f32_e32 v14, v48, v47
	v_fma_f32 v13, v13, v4, v45
	v_fma_f32 v19, v14, v7, v47
	v_add_f32_e32 v14, 1.0, v15
	v_rcp_f32_e32 v20, v14
	v_add_f32_e32 v14, 1.0, v18
	v_mul_f32_e32 v21, v13, v6
	v_rcp_f32_e32 v18, v14
	v_mul_f32_e32 v14, v21, v21
	v_or_b32_e32 v16, 1, v26
	s_nop 0
	v_mov_b32_dpp v14, v14 quad_perm:[1,0,3,2] row_mask:0xf bank_mask:0xf bound_ctrl:1
	v_fmac_f32_e32 v14, v21, v21
	s_nop 1
	v_add_f32_dpp v14, v14, v14 quad_perm:[2,3,0,1] row_mask:0xf bank_mask:0xf bound_ctrl:1
	s_nop 1
	v_add_f32_dpp v14, v14, v14 row_half_mirror row_mask:0xf bank_mask:0xf bound_ctrl:1
	s_nop 1
	v_add_f32_dpp v14, v14, v14 row_mirror row_mask:0xf bank_mask:0xf bound_ctrl:1
	s_nop 0
	v_readlane_b32 s3, v14, 16
	v_readlane_b32 s4, v14, 48
	v_readlane_b32 s0, v14, 0
	v_readlane_b32 s1, v14, 32
	v_mov_b32_e32 v14, s3
	v_mov_b32_e32 v15, s4
	v_pk_add_f32 v[14:15], s[0:1], v[14:15]
	s_movk_i32 s4, 0x44
	v_add_f32_e32 v14, v14, v15
	v_add_f32_e32 v14, 0x2b8cbccc, v14
	v_mul_f32_e32 v15, 0x4b800000, v14
	v_cmp_gt_f32_e64 s[0:1], s91, v14
	s_nop 1
	v_cndmask_b32_e64 v14, v14, v15, s[0:1]
	v_rsq_f32_e32 v14, v14
	v_mul_f32_e32 v15, 0xbf1b4598, v18
	v_mul_f32_e32 v15, 0x3fb8aa3b, v15
	v_exp_f32_e32 v15, v15
	v_mul_f32_e32 v18, 0x45800000, v14
	v_cndmask_b32_e64 v14, v14, v18, s[0:1]
	v_mul_f32_e32 v18, v21, v14
	v_add_f32_e32 v14, -1.0, v20
	v_fma_f32 v14, v3, v14, 1.0
	v_mul_f32_e32 v21, v13, v14
	v_mul_f32_e32 v13, v17, v21
	v_mul_f32_e32 v14, v2, v13
	v_mul_f32_e64 v23, v11, -v18
	s_nop 0
	v_mov_b32_dpp v14, v14 quad_perm:[1,0,3,2] row_mask:0xf bank_mask:0xf bound_ctrl:1
	v_fmac_f32_e32 v14, v2, v13
	s_nop 1
	v_add_f32_dpp v13, v14, v14 quad_perm:[2,3,0,1] row_mask:0xf bank_mask:0xf bound_ctrl:1
	s_nop 1
	v_add_f32_dpp v13, v13, v13 row_half_mirror row_mask:0xf bank_mask:0xf bound_ctrl:1
	s_nop 1
	v_add_f32_dpp v13, v13, v13 row_mirror row_mask:0xf bank_mask:0xf bound_ctrl:1
	s_nop 0
	v_readlane_b32 s0, v13, 0
	v_readlane_b32 s3, v13, 16
	v_readlane_b32 s1, v13, 32
	v_readlane_b32 s6, v13, 48
	v_mul_f32_e32 v13, v11, v15
	v_rcp_f32_e32 v22, v13
	v_mad_u64_u32 v[14:15], s[4:5], v16, s4, v[76:77]
	v_lshl_add_u32 v11, v14, 2, 0
	v_mul_f32_e32 v14, v17, v13
	ds_write2st64_b32 v11, v23, v14 offset1:68
	v_mul_f32_e32 v14, v20, v18
	v_mul_f32_e32 v14, v22, v14
	v_mul_f32_e32 v15, v22, v21
	ds_write2st64_b32 v11, v14, v15 offset0:136 offset1:204
	v_lshl_add_u32 v14, v16, 8, v12
	ds_write_b32 v14, v19
	s_and_saveexec_b64 s[4:5], vcc
	v_mov_b32_e32 v14, s3
	v_mov_b32_e32 v15, s6
	v_pk_add_f32 v[14:15], s[0:1], v[14:15]
	s_nop 0
	v_add_f32_e32 v14, v14, v15
	ds_write_b32 v10, v14 offset:4
	s_or_b64 exec, exec, s[4:5]
	v_add_f32_e32 v15, v58, v9
	v_mul_f32_e32 v15, 0xbfb8aa3b, v15
	v_add_f32_e32 v18, v109, v8
	v_exp_f32_e32 v15, v15
	v_mul_f32_e32 v18, 0xbfb8aa3b, v18
	v_sub_f32_e32 v14, v1, v52
	v_exp_f32_e32 v18, v18
	v_fma_f32 v16, v14, v5, v52
	v_sub_f32_e32 v14, v45, v54
	v_fma_f32 v17, v14, v4, v54
	v_sub_f32_e32 v14, v47, v56
	v_fma_f32 v19, v14, v7, v56
	v_add_f32_e32 v14, 1.0, v15
	v_rcp_f32_e32 v20, v14
	v_add_f32_e32 v14, 1.0, v18
	v_mul_f32_e32 v21, v17, v6
	v_rcp_f32_e32 v18, v14
	v_mul_f32_e32 v14, v21, v21
	v_lshl_add_u32 v12, v26, 8, v12
	s_nop 0
	v_mov_b32_dpp v14, v14 quad_perm:[1,0,3,2] row_mask:0xf bank_mask:0xf bound_ctrl:1
	v_fmac_f32_e32 v14, v21, v21
	s_nop 1
	v_add_f32_dpp v14, v14, v14 quad_perm:[2,3,0,1] row_mask:0xf bank_mask:0xf bound_ctrl:1
	s_nop 1
	v_add_f32_dpp v14, v14, v14 row_half_mirror row_mask:0xf bank_mask:0xf bound_ctrl:1
	s_nop 1
	v_add_f32_dpp v14, v14, v14 row_mirror row_mask:0xf bank_mask:0xf bound_ctrl:1
	s_nop 0
	v_readlane_b32 s3, v14, 16
	v_readlane_b32 s4, v14, 48
	v_readlane_b32 s0, v14, 0
	v_readlane_b32 s1, v14, 32
	v_mov_b32_e32 v14, s3
	v_mov_b32_e32 v15, s4
	v_pk_add_f32 v[14:15], s[0:1], v[14:15]
	s_nop 0
	v_add_f32_e32 v14, v14, v15
	v_add_f32_e32 v14, 0x2b8cbccc, v14
	v_mul_f32_e32 v15, 0x4b800000, v14
	v_cmp_gt_f32_e64 s[0:1], s91, v14
	s_nop 1
	v_cndmask_b32_e64 v14, v14, v15, s[0:1]
	v_rsq_f32_e32 v14, v14
	v_mul_f32_e32 v15, 0xbf1b4598, v18
	v_mul_f32_e32 v15, 0x3fb8aa3b, v15
	v_exp_f32_e32 v15, v15
	v_mul_f32_e32 v18, 0x45800000, v14
	v_cndmask_b32_e64 v14, v14, v18, s[0:1]
	v_mul_f32_e32 v18, v21, v14
	v_add_f32_e32 v14, -1.0, v20
	v_fma_f32 v14, v3, v14, 1.0
	v_mul_f32_e32 v17, v17, v14
	v_mul_f32_e32 v14, v16, v17
	v_mul_f32_e32 v21, v2, v14
	s_nop 1
	v_mov_b32_dpp v21, v21 quad_perm:[1,0,3,2] row_mask:0xf bank_mask:0xf bound_ctrl:1
	v_fmac_f32_e32 v21, v2, v14
	s_nop 1
	v_add_f32_dpp v14, v21, v21 quad_perm:[2,3,0,1] row_mask:0xf bank_mask:0xf bound_ctrl:1
	v_add_u32_e32 v21, 16, v11
	s_nop 0
	v_add_f32_dpp v14, v14, v14 row_half_mirror row_mask:0xf bank_mask:0xf bound_ctrl:1
	s_nop 1
	v_add_f32_dpp v14, v14, v14 row_mirror row_mask:0xf bank_mask:0xf bound_ctrl:1
	s_nop 0
	v_readlane_b32 s0, v14, 0
	v_readlane_b32 s3, v14, 16
	v_readlane_b32 s1, v14, 32
	v_readlane_b32 s6, v14, 48
	v_mul_f32_e32 v14, v15, v13
	v_rcp_f32_e32 v15, v14
	v_mul_f32_e64 v13, v13, -v18
	v_mul_f32_e32 v16, v16, v14
	ds_write2st64_b32 v21, v13, v16 offset0:1 offset1:69
	v_mul_f32_e32 v13, v20, v18
	v_mul_f32_e32 v13, v15, v13
	v_mul_f32_e32 v15, v17, v15
	ds_write2st64_b32 v21, v13, v15 offset0:137 offset1:205
	ds_write_b32 v12, v19 offset:512
	s_and_saveexec_b64 s[4:5], vcc
	v_mov_b32_e32 v16, s3
	v_mov_b32_e32 v17, s6
	v_pk_add_f32 v[16:17], s[0:1], v[16:17]
	s_nop 0
	v_add_f32_e32 v13, v16, v17
	ds_write_b32 v10, v13 offset:8
	s_or_b64 exec, exec, s[4:5]
	v_add_f32_e32 v17, v57, v9
	v_mul_f32_e32 v17, 0xbfb8aa3b, v17
	v_add_f32_e32 v18, v110, v8
	v_exp_f32_e32 v17, v17
	v_mul_f32_e32 v18, 0xbfb8aa3b, v18
	v_exp_f32_e32 v18, v18
	v_sub_f32_e32 v13, v52, v49
	v_fma_f32 v15, v13, v5, v49
	v_sub_f32_e32 v13, v54, v53
	v_sub_f32_e32 v16, v56, v55
	v_fma_f32 v13, v13, v4, v53
	v_fma_f32 v19, v16, v7, v55
	v_add_f32_e32 v16, 1.0, v17
	v_rcp_f32_e32 v20, v16
	v_add_f32_e32 v16, 1.0, v18
	v_mul_f32_e32 v21, v13, v6
	v_rcp_f32_e32 v18, v16
	v_mul_f32_e32 v16, v21, v21
	s_nop 1
	v_mov_b32_dpp v16, v16 quad_perm:[1,0,3,2] row_mask:0xf bank_mask:0xf bound_ctrl:1
	v_fmac_f32_e32 v16, v21, v21
	s_nop 1
	v_add_f32_dpp v16, v16, v16 quad_perm:[2,3,0,1] row_mask:0xf bank_mask:0xf bound_ctrl:1
	s_nop 1
	v_add_f32_dpp v16, v16, v16 row_half_mirror row_mask:0xf bank_mask:0xf bound_ctrl:1
	s_nop 1
	v_add_f32_dpp v16, v16, v16 row_mirror row_mask:0xf bank_mask:0xf bound_ctrl:1
	s_nop 0
	v_readlane_b32 s3, v16, 16
	v_readlane_b32 s4, v16, 48
	v_readlane_b32 s0, v16, 0
	v_readlane_b32 s1, v16, 32
	v_mov_b32_e32 v16, s3
	v_mov_b32_e32 v17, s4
	v_pk_add_f32 v[16:17], s[0:1], v[16:17]
	s_nop 0
	v_add_f32_e32 v16, v16, v17
	v_add_f32_e32 v16, 0x2b8cbccc, v16
	v_mul_f32_e32 v17, 0x4b800000, v16
	v_cmp_gt_f32_e64 s[0:1], s91, v16
	s_nop 1
	v_cndmask_b32_e64 v16, v16, v17, s[0:1]
	v_rsq_f32_e32 v16, v16
	v_mul_f32_e32 v17, 0xbf1b4598, v18
	v_mul_f32_e32 v17, 0x3fb8aa3b, v17
	v_exp_f32_e32 v17, v17
	v_mul_f32_e32 v18, 0x45800000, v16
	v_cndmask_b32_e64 v16, v16, v18, s[0:1]
	v_add_f32_e32 v18, -1.0, v20
	v_fma_f32 v18, v3, v18, 1.0
	v_mul_f32_e32 v18, v13, v18
	v_mul_f32_e32 v13, v15, v18
	v_mul_f32_e32 v16, v21, v16
	v_mul_f32_e32 v21, v2, v13
	s_nop 1
	v_mov_b32_dpp v21, v21 quad_perm:[1,0,3,2] row_mask:0xf bank_mask:0xf bound_ctrl:1
	v_fmac_f32_e32 v21, v2, v13
	s_nop 1
	v_add_f32_dpp v13, v21, v21 quad_perm:[2,3,0,1] row_mask:0xf bank_mask:0xf bound_ctrl:1
	v_add_u32_e32 v21, 32, v11
	s_nop 0
	v_add_f32_dpp v13, v13, v13 row_half_mirror row_mask:0xf bank_mask:0xf bound_ctrl:1
	s_nop 1
	v_add_f32_dpp v13, v13, v13 row_mirror row_mask:0xf bank_mask:0xf bound_ctrl:1
	s_nop 0
	v_readlane_b32 s0, v13, 0
	v_readlane_b32 s3, v13, 16
	v_readlane_b32 s1, v13, 32
	v_readlane_b32 s6, v13, 48
	v_mul_f32_e32 v13, v17, v14
	v_rcp_f32_e32 v17, v13
	v_mul_f32_e64 v14, v14, -v16
	v_mul_f32_e32 v15, v15, v13
	ds_write2st64_b32 v21, v14, v15 offset0:2 offset1:70
	v_mul_f32_e32 v14, v20, v16
	v_mul_f32_e32 v14, v17, v14
	v_mul_f32_e32 v15, v18, v17
	ds_write2st64_b32 v21, v14, v15 offset0:138 offset1:206
	ds_write_b32 v12, v19 offset:768
	s_and_saveexec_b64 s[4:5], vcc
	v_mov_b32_e32 v14, s3
	v_mov_b32_e32 v15, s6
	v_pk_add_f32 v[14:15], s[0:1], v[14:15]
	s_nop 0
	v_add_f32_e32 v14, v14, v15
	ds_write_b32 v10, v14 offset:12
	s_or_b64 exec, exec, s[4:5]
	v_add_f32_e32 v15, v66, v9
	v_mul_f32_e32 v15, 0xbfb8aa3b, v15
	v_add_f32_e32 v18, v111, v8
	v_exp_f32_e32 v15, v15
	v_mul_f32_e32 v18, 0xbfb8aa3b, v18
	v_sub_f32_e32 v14, v49, v60
	v_exp_f32_e32 v18, v18
	v_fma_f32 v16, v14, v5, v60
	v_sub_f32_e32 v14, v53, v62
	v_fma_f32 v17, v14, v4, v62
	v_sub_f32_e32 v14, v55, v64
	v_fma_f32 v19, v14, v7, v64
	v_add_f32_e32 v14, 1.0, v15
	v_rcp_f32_e32 v20, v14
	v_add_f32_e32 v14, 1.0, v18
	v_mul_f32_e32 v21, v17, v6
	v_rcp_f32_e32 v18, v14
	v_mul_f32_e32 v14, v21, v21
	s_nop 1
	v_mov_b32_dpp v14, v14 quad_perm:[1,0,3,2] row_mask:0xf bank_mask:0xf bound_ctrl:1
	v_fmac_f32_e32 v14, v21, v21
	s_nop 1
	v_add_f32_dpp v14, v14, v14 quad_perm:[2,3,0,1] row_mask:0xf bank_mask:0xf bound_ctrl:1
	s_nop 1
	v_add_f32_dpp v14, v14, v14 row_half_mirror row_mask:0xf bank_mask:0xf bound_ctrl:1
	s_nop 1
	v_add_f32_dpp v14, v14, v14 row_mirror row_mask:0xf bank_mask:0xf bound_ctrl:1
	s_nop 0
	v_readlane_b32 s3, v14, 16
	v_readlane_b32 s4, v14, 48
	v_readlane_b32 s0, v14, 0
	v_readlane_b32 s1, v14, 32
	v_mov_b32_e32 v14, s3
	v_mov_b32_e32 v15, s4
	v_pk_add_f32 v[14:15], s[0:1], v[14:15]
	s_nop 0
	v_add_f32_e32 v14, v14, v15
	v_add_f32_e32 v14, 0x2b8cbccc, v14
	v_mul_f32_e32 v15, 0x4b800000, v14
	v_cmp_gt_f32_e64 s[0:1], s91, v14
	s_nop 1
	v_cndmask_b32_e64 v14, v14, v15, s[0:1]
	v_rsq_f32_e32 v14, v14
	v_mul_f32_e32 v15, 0xbf1b4598, v18
	v_mul_f32_e32 v15, 0x3fb8aa3b, v15
	v_exp_f32_e32 v15, v15
	v_mul_f32_e32 v18, 0x45800000, v14
	v_cndmask_b32_e64 v14, v14, v18, s[0:1]
	v_mul_f32_e32 v18, v21, v14
	v_add_f32_e32 v14, -1.0, v20
	v_fma_f32 v14, v3, v14, 1.0
	v_mul_f32_e32 v17, v17, v14
	v_mul_f32_e32 v14, v16, v17
	v_mul_f32_e32 v21, v2, v14
	s_nop 1
	v_mov_b32_dpp v21, v21 quad_perm:[1,0,3,2] row_mask:0xf bank_mask:0xf bound_ctrl:1
	v_fmac_f32_e32 v21, v2, v14
	s_nop 1
	v_add_f32_dpp v14, v21, v21 quad_perm:[2,3,0,1] row_mask:0xf bank_mask:0xf bound_ctrl:1
	v_add_u32_e32 v21, 48, v11
	s_nop 0
	v_add_f32_dpp v14, v14, v14 row_half_mirror row_mask:0xf bank_mask:0xf bound_ctrl:1
	s_nop 1
	v_add_f32_dpp v14, v14, v14 row_mirror row_mask:0xf bank_mask:0xf bound_ctrl:1
	s_nop 0
	v_readlane_b32 s0, v14, 0
	v_readlane_b32 s3, v14, 16
	v_readlane_b32 s1, v14, 32
	v_readlane_b32 s6, v14, 48
	v_mul_f32_e32 v14, v15, v13
	v_rcp_f32_e32 v15, v14
	v_mul_f32_e64 v13, v13, -v18
	v_mul_f32_e32 v16, v16, v14
	ds_write2st64_b32 v21, v13, v16 offset0:3 offset1:71
	v_mul_f32_e32 v13, v20, v18
	v_mul_f32_e32 v13, v15, v13
	v_mul_f32_e32 v15, v17, v15
	ds_write2st64_b32 v21, v13, v15 offset0:139 offset1:207
	ds_write_b32 v12, v19 offset:1024
	s_and_saveexec_b64 s[4:5], vcc
	v_mov_b32_e32 v16, s3
	v_mov_b32_e32 v17, s6
	v_pk_add_f32 v[16:17], s[0:1], v[16:17]
	s_nop 0
	v_add_f32_e32 v13, v16, v17
	ds_write_b32 v10, v13 offset:16
	s_or_b64 exec, exec, s[4:5]
	v_add_f32_e32 v17, v65, v9
	v_mul_f32_e32 v17, 0xbfb8aa3b, v17
	v_add_f32_e32 v18, v112, v8
	v_exp_f32_e32 v17, v17
	v_mul_f32_e32 v18, 0xbfb8aa3b, v18
	v_exp_f32_e32 v18, v18
	v_sub_f32_e32 v13, v60, v59
	v_fma_f32 v15, v13, v5, v59
	v_sub_f32_e32 v13, v62, v61
	v_sub_f32_e32 v16, v64, v63
	v_fma_f32 v13, v13, v4, v61
	v_fma_f32 v19, v16, v7, v63
	v_add_f32_e32 v16, 1.0, v17
	v_rcp_f32_e32 v20, v16
	v_add_f32_e32 v16, 1.0, v18
	v_mul_f32_e32 v21, v13, v6
	v_rcp_f32_e32 v18, v16
	v_mul_f32_e32 v16, v21, v21
	s_nop 1
	v_mov_b32_dpp v16, v16 quad_perm:[1,0,3,2] row_mask:0xf bank_mask:0xf bound_ctrl:1
	v_fmac_f32_e32 v16, v21, v21
	s_nop 1
	v_add_f32_dpp v16, v16, v16 quad_perm:[2,3,0,1] row_mask:0xf bank_mask:0xf bound_ctrl:1
	s_nop 1
	v_add_f32_dpp v16, v16, v16 row_half_mirror row_mask:0xf bank_mask:0xf bound_ctrl:1
	s_nop 1
	v_add_f32_dpp v16, v16, v16 row_mirror row_mask:0xf bank_mask:0xf bound_ctrl:1
	s_nop 0
	v_readlane_b32 s3, v16, 16
	v_readlane_b32 s4, v16, 48
	v_readlane_b32 s0, v16, 0
	v_readlane_b32 s1, v16, 32
	v_mov_b32_e32 v16, s3
	v_mov_b32_e32 v17, s4
	v_pk_add_f32 v[16:17], s[0:1], v[16:17]
	s_nop 0
	v_add_f32_e32 v16, v16, v17
	v_add_f32_e32 v16, 0x2b8cbccc, v16
	v_mul_f32_e32 v17, 0x4b800000, v16
	v_cmp_gt_f32_e64 s[0:1], s91, v16
	s_nop 1
	v_cndmask_b32_e64 v16, v16, v17, s[0:1]
	v_rsq_f32_e32 v16, v16
	v_mul_f32_e32 v17, 0xbf1b4598, v18
	v_mul_f32_e32 v17, 0x3fb8aa3b, v17
	v_exp_f32_e32 v17, v17
	v_mul_f32_e32 v18, 0x45800000, v16
	v_cndmask_b32_e64 v16, v16, v18, s[0:1]
	v_add_f32_e32 v18, -1.0, v20
	v_fma_f32 v18, v3, v18, 1.0
	v_mul_f32_e32 v18, v13, v18
	v_mul_f32_e32 v13, v15, v18
	v_mul_f32_e32 v16, v21, v16
	v_mul_f32_e32 v21, v2, v13
	s_nop 1
	v_mov_b32_dpp v21, v21 quad_perm:[1,0,3,2] row_mask:0xf bank_mask:0xf bound_ctrl:1
	v_fmac_f32_e32 v21, v2, v13
	s_nop 1
	v_add_f32_dpp v13, v21, v21 quad_perm:[2,3,0,1] row_mask:0xf bank_mask:0xf bound_ctrl:1
	v_add_u32_e32 v21, 64, v11
	s_nop 0
	v_add_f32_dpp v13, v13, v13 row_half_mirror row_mask:0xf bank_mask:0xf bound_ctrl:1
	s_nop 1
	v_add_f32_dpp v13, v13, v13 row_mirror row_mask:0xf bank_mask:0xf bound_ctrl:1
	s_nop 0
	v_readlane_b32 s0, v13, 0
	v_readlane_b32 s3, v13, 16
	v_readlane_b32 s1, v13, 32
	v_readlane_b32 s6, v13, 48
	v_mul_f32_e32 v13, v17, v14
	v_rcp_f32_e32 v17, v13
	v_mul_f32_e64 v14, v14, -v16
	v_mul_f32_e32 v15, v15, v13
	ds_write2st64_b32 v21, v14, v15 offset0:4 offset1:72
	v_mul_f32_e32 v14, v20, v16
	v_mul_f32_e32 v14, v17, v14
	v_mul_f32_e32 v15, v18, v17
	ds_write2st64_b32 v21, v14, v15 offset0:140 offset1:208
	ds_write_b32 v12, v19 offset:1280
	s_and_saveexec_b64 s[4:5], vcc
	v_mov_b32_e32 v14, s3
	v_mov_b32_e32 v15, s6
	v_pk_add_f32 v[14:15], s[0:1], v[14:15]
	s_nop 0
	v_add_f32_e32 v14, v14, v15
	ds_write_b32 v10, v14 offset:20
	s_or_b64 exec, exec, s[4:5]
	v_add_f32_e32 v15, v74, v9
	v_mul_f32_e32 v15, 0xbfb8aa3b, v15
	v_add_f32_e32 v18, v113, v8
	v_exp_f32_e32 v15, v15
	v_mul_f32_e32 v18, 0xbfb8aa3b, v18
	v_sub_f32_e32 v14, v59, v67
	v_exp_f32_e32 v18, v18
	v_fma_f32 v16, v14, v5, v67
	v_sub_f32_e32 v14, v61, v69
	v_fma_f32 v17, v14, v4, v69
	v_sub_f32_e32 v14, v63, v71
	v_fma_f32 v19, v14, v7, v71
	v_add_f32_e32 v14, 1.0, v15
	v_rcp_f32_e32 v20, v14
	v_add_f32_e32 v14, 1.0, v18
	v_mul_f32_e32 v21, v17, v6
	v_rcp_f32_e32 v18, v14
	v_mul_f32_e32 v14, v21, v21
	s_nop 1
	v_mov_b32_dpp v14, v14 quad_perm:[1,0,3,2] row_mask:0xf bank_mask:0xf bound_ctrl:1
	v_fmac_f32_e32 v14, v21, v21
	s_nop 1
	v_add_f32_dpp v14, v14, v14 quad_perm:[2,3,0,1] row_mask:0xf bank_mask:0xf bound_ctrl:1
	s_nop 1
	v_add_f32_dpp v14, v14, v14 row_half_mirror row_mask:0xf bank_mask:0xf bound_ctrl:1
	s_nop 1
	v_add_f32_dpp v14, v14, v14 row_mirror row_mask:0xf bank_mask:0xf bound_ctrl:1
	s_nop 0
	v_readlane_b32 s3, v14, 16
	v_readlane_b32 s4, v14, 48
	v_readlane_b32 s0, v14, 0
	v_readlane_b32 s1, v14, 32
	v_mov_b32_e32 v14, s3
	v_mov_b32_e32 v15, s4
	v_pk_add_f32 v[14:15], s[0:1], v[14:15]
	s_nop 0
	v_add_f32_e32 v14, v14, v15
	v_add_f32_e32 v14, 0x2b8cbccc, v14
	v_mul_f32_e32 v15, 0x4b800000, v14
	v_cmp_gt_f32_e64 s[0:1], s91, v14
	s_nop 1
	v_cndmask_b32_e64 v14, v14, v15, s[0:1]
	v_rsq_f32_e32 v14, v14
	v_mul_f32_e32 v15, 0xbf1b4598, v18
	v_mul_f32_e32 v15, 0x3fb8aa3b, v15
	v_exp_f32_e32 v15, v15
	v_mul_f32_e32 v18, 0x45800000, v14
	v_cndmask_b32_e64 v14, v14, v18, s[0:1]
	v_mul_f32_e32 v18, v21, v14
	v_add_f32_e32 v14, -1.0, v20
	v_fma_f32 v14, v3, v14, 1.0
	v_mul_f32_e32 v17, v17, v14
	v_mul_f32_e32 v14, v16, v17
	v_mul_f32_e32 v21, v2, v14
	s_nop 1
	v_mov_b32_dpp v21, v21 quad_perm:[1,0,3,2] row_mask:0xf bank_mask:0xf bound_ctrl:1
	v_fmac_f32_e32 v21, v2, v14
	s_nop 1
	v_add_f32_dpp v14, v21, v21 quad_perm:[2,3,0,1] row_mask:0xf bank_mask:0xf bound_ctrl:1
	v_add_u32_e32 v21, 0x50, v11
	s_nop 0
	v_add_f32_dpp v14, v14, v14 row_half_mirror row_mask:0xf bank_mask:0xf bound_ctrl:1
	s_nop 1
	v_add_f32_dpp v14, v14, v14 row_mirror row_mask:0xf bank_mask:0xf bound_ctrl:1
	s_nop 0
	v_readlane_b32 s0, v14, 0
	v_readlane_b32 s3, v14, 16
	v_readlane_b32 s1, v14, 32
	v_readlane_b32 s6, v14, 48
	v_mul_f32_e32 v14, v15, v13
	v_rcp_f32_e32 v15, v14
	v_mul_f32_e64 v13, v13, -v18
	v_mul_f32_e32 v16, v16, v14
	ds_write2st64_b32 v21, v13, v16 offset0:5 offset1:73
	v_mul_f32_e32 v13, v20, v18
	v_mul_f32_e32 v13, v15, v13
	v_mul_f32_e32 v15, v17, v15
	ds_write2st64_b32 v21, v13, v15 offset0:141 offset1:209
	ds_write_b32 v12, v19 offset:1536
	s_and_saveexec_b64 s[4:5], vcc
	v_mov_b32_e32 v16, s3
	v_mov_b32_e32 v17, s6
	v_pk_add_f32 v[16:17], s[0:1], v[16:17]
	s_nop 0
	v_add_f32_e32 v13, v16, v17
	ds_write_b32 v10, v13 offset:24
	s_or_b64 exec, exec, s[4:5]
	v_sub_f32_e32 v13, v67, v68
	v_fma_f32 v13, v13, v5, v68
	v_sub_f32_e32 v5, v69, v70
	v_fma_f32 v15, v5, v4, v70
	v_add_f32_e32 v5, v73, v9
	v_mul_f32_e32 v5, 0xbfb8aa3b, v5
	v_add_f32_e32 v8, v114, v8
	v_exp_f32_e32 v5, v5
	v_mul_f32_e32 v8, 0xbfb8aa3b, v8
	v_exp_f32_e32 v8, v8
	v_sub_f32_e32 v4, v71, v72
	v_fma_f32 v7, v4, v7, v72
	v_add_f32_e32 v4, 1.0, v5
	v_rcp_f32_e32 v9, v4
	v_add_f32_e32 v4, 1.0, v8
	v_mul_f32_e32 v6, v15, v6
	v_rcp_f32_e32 v8, v4
	v_mul_f32_e32 v4, v6, v6
	v_add_u32_e32 v11, 0x60, v11
	s_nop 0
	v_mov_b32_dpp v4, v4 quad_perm:[1,0,3,2] row_mask:0xf bank_mask:0xf bound_ctrl:1
	v_fmac_f32_e32 v4, v6, v6
	s_nop 1
	v_add_f32_dpp v4, v4, v4 quad_perm:[2,3,0,1] row_mask:0xf bank_mask:0xf bound_ctrl:1
	s_nop 1
	v_add_f32_dpp v4, v4, v4 row_half_mirror row_mask:0xf bank_mask:0xf bound_ctrl:1
	s_nop 1
	v_add_f32_dpp v4, v4, v4 row_mirror row_mask:0xf bank_mask:0xf bound_ctrl:1
	s_nop 0
	v_readlane_b32 s3, v4, 16
	v_readlane_b32 s4, v4, 48
	v_readlane_b32 s0, v4, 0
	v_readlane_b32 s1, v4, 32
	v_mov_b32_e32 v4, s3
	v_mov_b32_e32 v5, s4
	v_pk_add_f32 v[4:5], s[0:1], v[4:5]
	s_nop 0
	v_add_f32_e32 v4, v4, v5
	v_add_f32_e32 v4, 0x2b8cbccc, v4
	v_mul_f32_e32 v5, 0x4b800000, v4
	v_cmp_gt_f32_e64 s[0:1], s91, v4
	s_nop 1
	v_cndmask_b32_e64 v4, v4, v5, s[0:1]
	v_rsq_f32_e32 v4, v4
	v_mul_f32_e32 v5, 0xbf1b4598, v8
	v_mul_f32_e32 v5, 0x3fb8aa3b, v5
	v_exp_f32_e32 v5, v5
	v_mul_f32_e32 v8, 0x45800000, v4
	v_cndmask_b32_e64 v4, v4, v8, s[0:1]
	v_mul_f32_e32 v4, v6, v4
	v_add_f32_e32 v6, -1.0, v9
	v_fma_f32 v3, v3, v6, 1.0
	v_mul_f32_e32 v3, v15, v3
	v_mul_f32_e32 v6, v13, v3
	v_mul_f32_e32 v8, v2, v6
	s_nop 1
	v_mov_b32_dpp v8, v8 quad_perm:[1,0,3,2] row_mask:0xf bank_mask:0xf bound_ctrl:1
	v_fmac_f32_e32 v8, v2, v6
	v_mul_f32_e64 v6, v14, -v4
	v_mul_f32_e32 v4, v9, v4
	v_add_f32_dpp v2, v8, v8 quad_perm:[2,3,0,1] row_mask:0xf bank_mask:0xf bound_ctrl:1
	s_nop 1
	v_add_f32_dpp v2, v2, v2 row_half_mirror row_mask:0xf bank_mask:0xf bound_ctrl:1
	s_nop 1
	v_add_f32_dpp v2, v2, v2 row_mirror row_mask:0xf bank_mask:0xf bound_ctrl:1
	s_nop 0
	v_readlane_b32 s0, v2, 0
	v_readlane_b32 s3, v2, 16
	v_readlane_b32 s1, v2, 32
	v_readlane_b32 s6, v2, 48
	v_mul_f32_e32 v2, v5, v14
	v_rcp_f32_e32 v5, v2
	v_mul_f32_e32 v8, v13, v2
	ds_write2st64_b32 v11, v6, v8 offset0:6 offset1:74
	v_mul_f32_e32 v4, v5, v4
	v_mul_f32_e32 v3, v3, v5
	ds_write2st64_b32 v11, v4, v3 offset0:142 offset1:210
	ds_write_b32 v12, v7 offset:1792
	s_and_saveexec_b64 s[4:5], vcc
	v_mov_b32_e32 v4, s3
	v_mov_b32_e32 v5, s6
	v_pk_add_f32 v[4:5], s[0:1], v[4:5]
	s_nop 0
	v_add_f32_e32 v3, v4, v5
	ds_write_b32 v10, v3 offset:28
	s_or_b64 exec, exec, s[4:5]
	v_lshlrev_b32_e32 v3, 8, v78
	v_lshlrev_b32_e32 v4, 2, v76
	v_add3_u32 v3, s92, v3, v4
	ds_write_b32 v3, v2
	v_and_b32_e32 v124, 15, v76
	v_lshrrev_b32_e32 v125, 4, v76
	v_and_b32_e32 v132, 7, v124
	v_add_u32_e32 v126, v26, v132
	v_mul_u32_u24_e32 v126, 0x110, v126
	v_lshl_add_u32 v126, v125, 4, v126
	v_and_b32_e32 v127, 8, v124
	v_mul_u32_u24_e32 v127, 0x880, v127
	v_add_u32_e32 v128, v126, v127
	v_add_u32_e32 v129, 0x8800, v128
	ds_read_b128 v[136:139], v128 offset:0
	ds_read_b128 v[152:155], v129 offset:0
	ds_read_b128 v[140:143], v128 offset:64
	ds_read_b128 v[156:159], v129 offset:64
	ds_read_b128 v[144:147], v128 offset:128
	ds_read_b128 v[160:163], v129 offset:128
	ds_read_b128 v[148:151], v128 offset:192
	ds_read_b128 v[164:167], v129 offset:192
	v_lshrrev_b32_e32 v126, 1, v125
	v_lshrrev_b32_e32 v127, 3, v124
	v_lshl_add_u32 v127, v126, 1, v127
	v_lshlrev_b32_e32 v130, 8, v127
	v_lshl_add_u32 v130, v26, 7, v130
	v_and_b32_e32 v127, 1, v125
	v_lshl_add_u32 v130, v127, 7, v130
	v_lshl_add_u32 v130, v132, 2, v130
	v_add_u32_e32 v130, 0x15800, v130
	v_sub_u32_e32 v131, 1, v126
	v_add_u32_e32 v131, v131, v132
	v_lshlrev_b32_e32 v127, 2, v127
	v_sub_u32_e32 v131, v131, v127
	v_max_i32_e32 v131, 0, v131
	v_cmp_ge_u32_e64 s[0:1], 1, v131
	v_cmp_ge_u32_e64 s[4:5], 2, v131
	v_cmp_ge_u32_e64 s[6:7], 3, v131
	v_cmp_ge_u32_e32 vcc, 0, v131
	s_waitcnt lgkmcnt(0)
	v_mfma_f32_16x16x4_f32 v[36:39], v136, v152, 0
	v_mfma_f32_16x16x4_f32 v[40:43], v137, v153, 0
	v_mfma_f32_16x16x4_f32 v[36:39], v138, v154, v[36:39]
	v_mfma_f32_16x16x4_f32 v[40:43], v139, v155, v[40:43]
	v_mfma_f32_16x16x4_f32 v[36:39], v140, v156, v[36:39]
	v_mfma_f32_16x16x4_f32 v[40:43], v141, v157, v[40:43]
	v_mfma_f32_16x16x4_f32 v[36:39], v142, v158, v[36:39]
	v_mfma_f32_16x16x4_f32 v[40:43], v143, v159, v[40:43]
	v_mfma_f32_16x16x4_f32 v[36:39], v144, v160, v[36:39]
	v_mfma_f32_16x16x4_f32 v[40:43], v145, v161, v[40:43]
	v_mfma_f32_16x16x4_f32 v[36:39], v146, v162, v[36:39]
	v_mfma_f32_16x16x4_f32 v[40:43], v147, v163, v[40:43]
	v_mfma_f32_16x16x4_f32 v[36:39], v148, v164, v[36:39]
	v_mfma_f32_16x16x4_f32 v[40:43], v149, v165, v[40:43]
	v_mfma_f32_16x16x4_f32 v[36:39], v150, v166, v[36:39]
	v_mfma_f32_16x16x4_f32 v[40:43], v151, v167, v[40:43]
	s_nop 7
	s_nop 2
	v_pk_add_f32 v[36:37], v[36:37], v[40:41]
	v_pk_add_f32 v[38:39], v[38:39], v[42:43]
	v_cndmask_b32_e32 v36, 0, v36, vcc
	v_cndmask_b32_e64 v37, 0, v37, s[0:1]
	v_cndmask_b32_e64 v38, 0, v38, s[4:5]
	v_cndmask_b32_e64 v39, 0, v39, s[6:7]
	ds_write_b32 v130, v36 offset:0
	ds_write_b32 v130, v37 offset:32
	ds_write_b32 v130, v38 offset:64
	ds_write_b32 v130, v39 offset:96
	v_mov_b32_e32 v168, v132
	v_lshlrev_b32_e32 v169, 7, v26
	v_add_u32_e32 v169, 0x15800, v169
	v_lshl_add_u32 v172, v125, 6, v169
	v_lshl_add_u32 v170, v132, 2, v169
	v_lshl_add_u32 v173, v132, 2, v172
	v_mov_b32_e32 v171, 1.0
	ds_read_b128 v[124:127], v169 offset:32
	ds_read_b128 v[128:131], v169 offset:64
	ds_read_b128 v[132:135], v169 offset:96
	ds_read_b128 v[136:139], v169 offset:128
	ds_read_b128 v[144:147], v169 offset:160
	ds_read_b128 v[148:151], v169 offset:176
	ds_read_b128 v[152:155], v169 offset:192
	ds_read_b128 v[156:159], v169 offset:208
	ds_read_b128 v[160:163], v169 offset:224
	ds_read_b128 v[164:167], v169 offset:240
	ds_read_b128 v[182:185], v172 offset:512
	ds_read_b128 v[186:189], v172 offset:528
	ds_read_b128 v[190:193], v172 offset:544
	ds_read_b128 v[194:197], v172 offset:560
	v_cmp_eq_u32_e32 vcc, 0, v168
	v_cndmask_b32_e32 v36, 0, v171, vcc
	v_cmp_eq_u32_e32 vcc, 1, v168
	v_cndmask_b32_e32 v37, 0, v171, vcc
	v_cmp_eq_u32_e32 vcc, 2, v168
	v_cndmask_b32_e32 v38, 0, v171, vcc
	v_cmp_eq_u32_e32 vcc, 3, v168
	v_cndmask_b32_e32 v39, 0, v171, vcc
	v_cmp_eq_u32_e32 vcc, 4, v168
	v_cndmask_b32_e32 v40, 0, v171, vcc
	v_cmp_eq_u32_e32 vcc, 5, v168
	v_cndmask_b32_e32 v41, 0, v171, vcc
	v_cmp_eq_u32_e32 vcc, 6, v168
	v_cndmask_b32_e32 v42, 0, v171, vcc
	v_cmp_eq_u32_e32 vcc, 7, v168
	v_cndmask_b32_e32 v43, 0, v171, vcc
	s_waitcnt lgkmcnt(0)
	v_fmac_f32_e32 v37, v124, v36
	v_fmac_f32_e32 v38, v128, v36
	v_fmac_f32_e32 v39, v132, v36
	v_fmac_f32_e32 v40, v136, v36
	v_fmac_f32_e32 v41, v144, v36
	v_fmac_f32_e32 v42, v152, v36
	v_fmac_f32_e32 v43, v160, v36
	v_fmac_f32_e32 v38, v129, v37
	v_fmac_f32_e32 v39, v133, v37
	v_fmac_f32_e32 v40, v137, v37
	v_fmac_f32_e32 v41, v145, v37
	v_fmac_f32_e32 v42, v153, v37
	v_fmac_f32_e32 v43, v161, v37
	v_fmac_f32_e32 v39, v134, v38
	v_fmac_f32_e32 v40, v138, v38
	v_fmac_f32_e32 v41, v146, v38
	v_fmac_f32_e32 v42, v154, v38
	v_fmac_f32_e32 v43, v162, v38
	v_fmac_f32_e32 v40, v139, v39
	v_fmac_f32_e32 v41, v147, v39
	v_fmac_f32_e32 v42, v155, v39
	v_fmac_f32_e32 v43, v163, v39
	v_fmac_f32_e32 v41, v148, v40
	v_fmac_f32_e32 v42, v156, v40
	v_fmac_f32_e32 v43, v164, v40
	v_fmac_f32_e32 v42, v157, v41
	v_fmac_f32_e32 v43, v165, v41
	v_fmac_f32_e32 v43, v166, v42
	v_mul_f32_e32 v44, v182, v36
	v_fmac_f32_e32 v44, v183, v37
	v_fmac_f32_e32 v44, v184, v38
	v_fmac_f32_e32 v44, v185, v39
	v_fmac_f32_e32 v44, v186, v40
	v_fmac_f32_e32 v44, v187, v41
	v_fmac_f32_e32 v44, v188, v42
	v_fmac_f32_e32 v44, v189, v43
	v_mul_f32_e32 v45, v190, v36
	v_fmac_f32_e32 v45, v191, v37
	v_fmac_f32_e32 v45, v192, v38
	v_fmac_f32_e32 v45, v193, v39
	v_fmac_f32_e32 v45, v194, v40
	v_fmac_f32_e32 v45, v195, v41
	v_fmac_f32_e32 v45, v196, v42
	v_fmac_f32_e32 v45, v197, v43
	ds_write_b32 v170, v36 offset:0
	ds_write_b32 v170, v37 offset:32
	ds_write_b32 v170, v38 offset:64
	ds_write_b32 v170, v39 offset:96
	ds_write_b32 v170, v40 offset:128
	ds_write_b32 v170, v41 offset:160
	ds_write_b32 v170, v42 offset:192
	ds_write_b32 v170, v43 offset:224
	ds_write_b32 v173, v44 offset:512
	ds_write_b32 v173, v45 offset:544
	s_lshl_b32 s17, s40, 6
	s_cmp_lg_u32 s40, 31
	s_waitcnt lgkmcnt(0)
	s_barrier
	s_cbranch_scc0 .LBB0_586
	v_readfirstlane_b32 s0, v180
	s_nop 1
	s_cmpk_ge_u32 s0, 0x100
	s_cbranch_scc1 .LBB0_586
	s_add_i32 s3, s17, 64
	s_add_u32 s0, s80, s3
	s_addc_u32 s1, s81, 0
	v_ashrrev_i32_e32 v27, 31, v26
	v_lshl_add_u64 v[4:5], s[0:1], 0, v[26:27]
	v_mad_u64_u32 v[2:3], s[0:1], v4, s83, 0
	v_mad_i32_i24 v3, v5, s83, v3
	v_add_u32_e32 v1, s3, v26
	v_mov_b32_e32 v95, v94
	v_lshl_add_u64 v[2:3], s[46:47], 0, v[2:3]
	v_cmp_lt_i32_e32 vcc, 0, v1
	v_mov_b32_e32 v106, 0
	v_lshl_add_u64 v[2:3], v[28:29], 1, v[2:3]
	v_mov_b64_e32 v[34:35], v[94:95]
	s_and_saveexec_b64 s[0:1], vcc
	s_cbranch_execz .LBB0_585
	global_load_ushort v52, v[2:3], off offset:-3072
	global_load_ushort v53, v[2:3], off offset:-2048
	global_load_ushort v54, v[2:3], off offset:-1024

.Lrw_go_0:
	s_waitcnt vmcnt(0)
	ds_read_b32 v150, v146 offset:0
	ds_read_b32 v152, v147 offset:0
	ds_read_b32 v154, v148 offset:0
	ds_read_b32 v151, v146 offset:1024
	ds_read_b32 v153, v147 offset:1024
	ds_read_b32 v155, v148 offset:16
	v_lshlrev_b32_e32 v128, 16, v128
	v_lshlrev_b32_e32 v129, 16, v129
	s_waitcnt lgkmcnt(0)
	v_mov_b32_e32 v156, v150
	v_mov_b32_e32 v157, v151
	s_nop 0
	v_add_f32_dpp v156, v156, v156 quad_perm:[1,0,3,2] row_mask:0xf bank_mask:0xf bound_ctrl:1
	v_add_f32_dpp v157, v157, v157 quad_perm:[1,0,3,2] row_mask:0xf bank_mask:0xf bound_ctrl:1
	s_nop 0
	v_add_f32_dpp v156, v156, v156 quad_perm:[2,3,0,1] row_mask:0xf bank_mask:0xf bound_ctrl:1
	v_add_f32_dpp v157, v157, v157 quad_perm:[2,3,0,1] row_mask:0xf bank_mask:0xf bound_ctrl:1
	s_nop 0
	v_add_f32_dpp v156, v156, v156 row_half_mirror row_mask:0xf bank_mask:0xf bound_ctrl:1
	v_add_f32_dpp v157, v157, v157 row_half_mirror row_mask:0xf bank_mask:0xf bound_ctrl:1
	s_nop 0
	v_add_f32_dpp v156, v156, v156 row_mirror row_mask:0xf bank_mask:0xf bound_ctrl:1
	v_add_f32_dpp v157, v157, v157 row_mirror row_mask:0xf bank_mask:0xf bound_ctrl:1
	s_nop 0
	v_add_f32_dpp v156, v156, v156 row_bcast:15 row_mask:0xa bank_mask:0xf
	v_add_f32_dpp v157, v157, v157 row_bcast:15 row_mask:0xa bank_mask:0xf
	s_nop 0
	v_add_f32_dpp v156, v156, v156 row_bcast:31 row_mask:0xc bank_mask:0xf
	v_add_f32_dpp v157, v157, v157 row_bcast:31 row_mask:0xc bank_mask:0xf
	s_nop 0
	v_readlane_b32 s4, v156, 63
	v_readlane_b32 s5, v157, 63
	s_nop 1
	v_fmac_f32_e32 v150, s4, v125
	v_fmac_f32_e32 v151, s5, v125
	v_mul_f32_e32 v158, v150, v150
	v_mul_f32_e32 v159, v151, v151
	v_mul_f32_e32 v162, 0xbfb8aa3b, v128
	v_exp_f32_e32 v162, v162
	v_mul_f32_e32 v163, 0xbfb8aa3b, v129
	v_exp_f32_e32 v163, v163
	v_add_f32_dpp v158, v158, v158 quad_perm:[1,0,3,2] row_mask:0xf bank_mask:0xf bound_ctrl:1
	v_add_f32_dpp v159, v159, v159 quad_perm:[1,0,3,2] row_mask:0xf bank_mask:0xf bound_ctrl:1
	s_nop 0
	v_add_f32_dpp v158, v158, v158 quad_perm:[2,3,0,1] row_mask:0xf bank_mask:0xf bound_ctrl:1
	v_add_f32_dpp v159, v159, v159 quad_perm:[2,3,0,1] row_mask:0xf bank_mask:0xf bound_ctrl:1
	s_nop 0
	v_add_f32_dpp v158, v158, v158 row_half_mirror row_mask:0xf bank_mask:0xf bound_ctrl:1
	v_add_f32_dpp v159, v159, v159 row_half_mirror row_mask:0xf bank_mask:0xf bound_ctrl:1
	s_nop 0
	v_add_f32_dpp v158, v158, v158 row_mirror row_mask:0xf bank_mask:0xf bound_ctrl:1
	v_add_f32_dpp v159, v159, v159 row_mirror row_mask:0xf bank_mask:0xf bound_ctrl:1
	s_nop 0
	v_add_f32_dpp v158, v158, v158 row_bcast:15 row_mask:0xa bank_mask:0xf
	v_add_f32_dpp v159, v159, v159 row_bcast:15 row_mask:0xa bank_mask:0xf
	s_nop 0
	v_add_f32_dpp v158, v158, v158 row_bcast:31 row_mask:0xc bank_mask:0xf
	v_add_f32_dpp v159, v159, v159 row_bcast:31 row_mask:0xc bank_mask:0xf
	s_nop 0
	v_readlane_b32 s6, v158, 63
	v_readlane_b32 s7, v159, 63
	v_add_f32_e32 v162, 1.0, v162
	v_rcp_f32_e32 v162, v162
	v_add_f32_e32 v163, 1.0, v163
	v_rcp_f32_e32 v163, v163
	v_fma_f32 v160, s6, v126, v127
	v_fma_f32 v161, s7, v126, v127
	v_rsq_f32_e32 v160, v160
	v_rsq_f32_e32 v161, v161
	s_nop 0
	v_mul_f32_e32 v164, v150, v160
	v_fma_f32 v164, v144, v164, v145
	v_fmac_f32_e32 v164, v154, v152
	v_mul_f32_e32 v164, v164, v128
	v_mul_f32_e32 v164, v162, v164
	v_mul_f32_e32 v165, v151, v161
	v_fma_f32 v165, v144, v165, v145
	v_fmac_f32_e32 v165, v155, v153
	v_mul_f32_e32 v165, v165, v129
	v_mul_f32_e32 v165, v163, v165
	v_bfe_u32 v156, v164, 16, 1
	v_add3_u32 v164, v164, v156, s97
	v_bfe_u32 v157, v165, 16, 1
	v_add3_u32 v165, v165, v157, s97
	global_store_short_d16_hi v124, v164, s[12:13]
	s_add_u32 s12, s12, 0x1000
	s_addc_u32 s13, s13, 0
	global_store_short_d16_hi v124, v165, s[12:13]
	s_add_u32 s12, s12, 0x1000
	s_addc_u32 s13, s13, 0
	s_cmp_lg_u32 s40, 31
	s_cbranch_scc0 .Lrw_nopf
	s_add_i32 s3, s17, 64
	s_add_u32 s0, s80, s3
	s_addc_u32 s1, s81, 0
	v_ashrrev_i32_e32 v27, 31, v26
	v_lshl_add_u64 v[4:5], s[0:1], 0, v[26:27]
	v_mad_u64_u32 v[2:3], s[0:1], v4, s83, 0
	v_mad_i32_i24 v3, v5, s83, v3
	v_add_u32_e32 v1, s3, v26
	v_mov_b32_e32 v95, v94
	v_lshl_add_u64 v[2:3], s[46:47], 0, v[2:3]
	v_cmp_lt_i32_e32 vcc, 0, v1
	v_mov_b32_e32 v106, 0
	v_lshl_add_u64 v[2:3], v[28:29], 1, v[2:3]
	v_mov_b64_e32 v[34:35], v[94:95]
	s_and_saveexec_b64 s[0:1], vcc
	s_cbranch_execz .Lrw_pf585
	global_load_ushort v52, v[2:3], off offset:-3072
	global_load_ushort v53, v[2:3], off offset:-2048
	global_load_ushort v54, v[2:3], off offset:-1024

.Lrw_nopf:
.Lrw_poll_1:
	ds_read_b32 v156, v149 offset:4
	s_waitcnt lgkmcnt(0)
	v_readfirstlane_b32 s14, v156
	s_cmp_ge_u32 s14, s15
	s_cbranch_scc1 .Lrw_go_1
	s_sleep 2
	s_branch .Lrw_poll_1

.Lrw_go_7:
	ds_read_b32 v150, v146 offset:14336
	ds_read_b32 v152, v147 offset:14336
	ds_read_b32 v154, v148 offset:224
	ds_read_b32 v151, v146 offset:15360
	ds_read_b32 v153, v147 offset:15360
	ds_read_b32 v155, v148 offset:240
	v_lshlrev_b32_e32 v142, 16, v142
	v_lshlrev_b32_e32 v143, 16, v143
	s_waitcnt lgkmcnt(0)
	v_mov_b32_e32 v156, v150
	v_mov_b32_e32 v157, v151
	s_nop 0
	v_add_f32_dpp v156, v156, v156 quad_perm:[1,0,3,2] row_mask:0xf bank_mask:0xf bound_ctrl:1
	v_add_f32_dpp v157, v157, v157 quad_perm:[1,0,3,2] row_mask:0xf bank_mask:0xf bound_ctrl:1
	s_nop 0
	v_add_f32_dpp v156, v156, v156 quad_perm:[2,3,0,1] row_mask:0xf bank_mask:0xf bound_ctrl:1
	v_add_f32_dpp v157, v157, v157 quad_perm:[2,3,0,1] row_mask:0xf bank_mask:0xf bound_ctrl:1
	s_nop 0
	v_add_f32_dpp v156, v156, v156 row_half_mirror row_mask:0xf bank_mask:0xf bound_ctrl:1
	v_add_f32_dpp v157, v157, v157 row_half_mirror row_mask:0xf bank_mask:0xf bound_ctrl:1
	s_nop 0
	v_add_f32_dpp v156, v156, v156 row_mirror row_mask:0xf bank_mask:0xf bound_ctrl:1
	v_add_f32_dpp v157, v157, v157 row_mirror row_mask:0xf bank_mask:0xf bound_ctrl:1
	s_nop 0
	v_add_f32_dpp v156, v156, v156 row_bcast:15 row_mask:0xa bank_mask:0xf
	v_add_f32_dpp v157, v157, v157 row_bcast:15 row_mask:0xa bank_mask:0xf
	s_nop 0
	v_add_f32_dpp v156, v156, v156 row_bcast:31 row_mask:0xc bank_mask:0xf
	v_add_f32_dpp v157, v157, v157 row_bcast:31 row_mask:0xc bank_mask:0xf
	s_nop 0
	v_readlane_b32 s4, v156, 63
	v_readlane_b32 s5, v157, 63
	s_nop 1
	v_fmac_f32_e32 v150, s4, v125
	v_fmac_f32_e32 v151, s5, v125
	v_mul_f32_e32 v158, v150, v150
	v_mul_f32_e32 v159, v151, v151
	v_mul_f32_e32 v162, 0xbfb8aa3b, v142
	v_exp_f32_e32 v162, v162
	v_mul_f32_e32 v163, 0xbfb8aa3b, v143
	v_exp_f32_e32 v163, v163
	v_add_f32_dpp v158, v158, v158 quad_perm:[1,0,3,2] row_mask:0xf bank_mask:0xf bound_ctrl:1
	v_add_f32_dpp v159, v159, v159 quad_perm:[1,0,3,2] row_mask:0xf bank_mask:0xf bound_ctrl:1
	s_nop 0
	v_add_f32_dpp v158, v158, v158 quad_perm:[2,3,0,1] row_mask:0xf bank_mask:0xf bound_ctrl:1
	v_add_f32_dpp v159, v159, v159 quad_perm:[2,3,0,1] row_mask:0xf bank_mask:0xf bound_ctrl:1
	s_nop 0
	v_add_f32_dpp v158, v158, v158 row_half_mirror row_mask:0xf bank_mask:0xf bound_ctrl:1
	v_add_f32_dpp v159, v159, v159 row_half_mirror row_mask:0xf bank_mask:0xf bound_ctrl:1
	s_nop 0
	v_add_f32_dpp v158, v158, v158 row_mirror row_mask:0xf bank_mask:0xf bound_ctrl:1
	v_add_f32_dpp v159, v159, v159 row_mirror row_mask:0xf bank_mask:0xf bound_ctrl:1
	s_nop 0
	v_add_f32_dpp v158, v158, v158 row_bcast:15 row_mask:0xa bank_mask:0xf
	v_add_f32_dpp v159, v159, v159 row_bcast:15 row_mask:0xa bank_mask:0xf
	s_nop 0
	v_add_f32_dpp v158, v158, v158 row_bcast:31 row_mask:0xc bank_mask:0xf
	v_add_f32_dpp v159, v159, v159 row_bcast:31 row_mask:0xc bank_mask:0xf
	s_nop 0
	v_readlane_b32 s6, v158, 63
	v_readlane_b32 s7, v159, 63
	v_add_f32_e32 v162, 1.0, v162
	v_rcp_f32_e32 v162, v162
	v_add_f32_e32 v163, 1.0, v163
	v_rcp_f32_e32 v163, v163
	v_fma_f32 v160, s6, v126, v127
	v_fma_f32 v161, s7, v126, v127
	v_rsq_f32_e32 v160, v160
	v_rsq_f32_e32 v161, v161
	s_nop 0
	v_mul_f32_e32 v164, v150, v160
	v_fma_f32 v164, v144, v164, v145
	v_fmac_f32_e32 v164, v154, v152
	v_mul_f32_e32 v164, v164, v142
	v_mul_f32_e32 v164, v162, v164
	v_mul_f32_e32 v165, v151, v161
	v_fma_f32 v165, v144, v165, v145
	v_fmac_f32_e32 v165, v155, v153
	v_mul_f32_e32 v165, v165, v143
	v_mul_f32_e32 v165, v163, v165
	v_bfe_u32 v156, v164, 16, 1
	v_add3_u32 v164, v164, v156, s97
	v_bfe_u32 v157, v165, 16, 1
	v_add3_u32 v165, v165, v157, s97
	global_store_short_d16_hi v124, v164, s[12:13]
	s_add_u32 s12, s12, 0x1000
	s_addc_u32 s13, s13, 0
	global_store_short_d16_hi v124, v165, s[12:13]
	s_add_u32 s12, s12, 0x1000
	s_addc_u32 s13, s13, 0
	s_cmp_lg_u32 s40, 31
	s_cbranch_scc0 .Lrw_noladder
	s_waitcnt vmcnt(14)
	v_lshlrev_b32_e32 v106, 16, v52
	v_lshlrev_b32_e32 v35, 16, v53
	v_lshlrev_b32_e32 v34, 16, v54
	v_lshlrev_b32_e32 v44, 16, v18
	v_lshlrev_b32_e32 v1, 16, v1
	v_lshlrev_b32_e32 v46, 16, v19
	v_lshlrev_b32_e32 v48, 16, v20
	v_lshlrev_b32_e32 v45, 16, v21
	v_lshlrev_b32_e32 v47, 16, v22
	v_lshlrev_b32_e32 v51, 16, v23
	v_lshlrev_b32_e32 v54, 16, v24
	v_lshlrev_b32_e32 v52, 16, v25
	v_lshlrev_b32_e32 v50, 16, v27
	v_lshlrev_b32_e32 v49, 16, v28
	v_lshlrev_b32_e32 v53, 16, v29
	v_lshlrev_b32_e32 v57, 16, v31
	v_lshlrev_b32_e32 v60, 16, v32
	v_lshlrev_b32_e32 v58, 16, v33
	v_lshlrev_b32_e32 v56, 16, v55
	v_lshlrev_b32_e32 v55, 16, v30
	v_lshlrev_b32_e32 v59, 16, v59
	v_lshlrev_b32_e32 v61, 16, v61
	v_lshlrev_b32_e32 v62, 16, v62
	v_lshlrev_b32_e32 v63, 16, v63
	v_lshlrev_b32_e32 v66, 16, v66
	v_lshlrev_b32_e32 v64, 16, v64
	v_lshlrev_b32_e32 v65, 16, v6
	v_lshlrev_b32_e32 v67, 16, v7
	v_lshlrev_b32_e32 v70, 16, v12
	v_lshlrev_b32_e32 v72, 16, v13
	v_lshlrev_b32_e32 v68, 16, v16
	v_lshlrev_b32_e32 v69, 16, v17
	v_lshlrev_b32_e32 v71, 16, v8
	v_lshlrev_b32_e32 v74, 16, v9
	v_lshlrev_b32_e32 v73, 16, v4
	s_branch .Lrw_noladder
.Lrw_done:
	s_cmp_lg_u32 s40, 31
	s_cbranch_scc0 .Lrw_noladder
	s_waitcnt vmcnt(39)
	v_lshlrev_b32_e32 v106, 16, v52
	v_lshlrev_b32_e32 v35, 16, v53
	v_lshlrev_b32_e32 v34, 16, v54
	v_lshlrev_b32_e32 v44, 16, v18
	s_waitcnt vmcnt(38)
	v_lshlrev_b32_e32 v1, 16, v1
	s_waitcnt vmcnt(37)
	v_lshlrev_b32_e32 v46, 16, v19
	s_waitcnt vmcnt(36)
	v_lshlrev_b32_e32 v48, 16, v20
	s_waitcnt vmcnt(34)
	v_lshlrev_b32_e32 v45, 16, v21
	s_waitcnt vmcnt(33)
	v_lshlrev_b32_e32 v47, 16, v22
	s_waitcnt vmcnt(32)
	v_lshlrev_b32_e32 v51, 16, v23
	s_waitcnt vmcnt(30)
	v_lshlrev_b32_e32 v54, 16, v24
	s_waitcnt vmcnt(29)
	v_lshlrev_b32_e32 v52, 16, v25
	s_waitcnt vmcnt(28)
	v_lshlrev_b32_e32 v50, 16, v27
	s_waitcnt vmcnt(26)
	v_lshlrev_b32_e32 v49, 16, v28
	s_waitcnt vmcnt(25)
	v_lshlrev_b32_e32 v53, 16, v29
	s_waitcnt vmcnt(23)
	v_lshlrev_b32_e32 v57, 16, v31
	s_waitcnt vmcnt(22)
	v_lshlrev_b32_e32 v60, 16, v32
	s_waitcnt vmcnt(21)
	v_lshlrev_b32_e32 v58, 16, v33
	s_waitcnt vmcnt(20)
	v_lshlrev_b32_e32 v56, 16, v55
	v_lshlrev_b32_e32 v55, 16, v30
	s_waitcnt vmcnt(17)
	v_lshlrev_b32_e32 v59, 16, v59
	s_waitcnt vmcnt(16)
	v_lshlrev_b32_e32 v61, 16, v61
	s_waitcnt vmcnt(15)
	v_lshlrev_b32_e32 v62, 16, v62
	s_waitcnt vmcnt(14)
	v_lshlrev_b32_e32 v63, 16, v63
	s_waitcnt vmcnt(13)
	v_lshlrev_b32_e32 v66, 16, v66
	s_waitcnt vmcnt(12)
	v_lshlrev_b32_e32 v64, 16, v64
	s_waitcnt vmcnt(11)
	v_lshlrev_b32_e32 v65, 16, v6
	s_waitcnt vmcnt(9)
	v_lshlrev_b32_e32 v67, 16, v7
	s_waitcnt vmcnt(8)
	v_lshlrev_b32_e32 v70, 16, v12
	s_waitcnt vmcnt(7)
	v_lshlrev_b32_e32 v72, 16, v13
	s_waitcnt vmcnt(6)
	v_lshlrev_b32_e32 v68, 16, v16
	s_waitcnt vmcnt(5)
	v_lshlrev_b32_e32 v69, 16, v17
	s_waitcnt vmcnt(4)
	v_lshlrev_b32_e32 v71, 16, v8
	s_waitcnt vmcnt(2)
	v_lshlrev_b32_e32 v74, 16, v9
	s_waitcnt vmcnt(1)
	v_lshlrev_b32_e32 v73, 16, v4
	s_waitcnt vmcnt(0)

.LBB0_764:
	s_waitcnt vmcnt(0)
	v_mov_b32_e32 v127, 0
	s_andn2_b64 vcc, exec, s[14:15]
	v_mov_b32_e32 v126, v127
	v_mov_b32_e32 v125, v127
	v_mov_b32_e32 v124, v127
	v_mov_b32_e32 v123, v127
	v_mov_b32_e32 v122, v127
	v_mov_b32_e32 v121, v127
	v_mov_b32_e32 v120, v127
	v_mov_b32_e32 v111, v127
	v_mov_b32_e32 v110, v127
	v_mov_b32_e32 v109, v127
	v_mov_b32_e32 v108, v127
	v_mov_b32_e32 v107, v127
	v_mov_b32_e32 v106, v127
	v_mov_b32_e32 v105, v127
	v_mov_b32_e32 v104, v127
	v_mov_b32_e32 v95, v127
	v_mov_b32_e32 v94, v127
	v_mov_b32_e32 v93, v127
	v_mov_b32_e32 v92, v127
	v_mov_b32_e32 v91, v127
	v_mov_b32_e32 v90, v127
	v_mov_b32_e32 v89, v127
	v_mov_b32_e32 v88, v127
	v_mov_b32_e32 v79, v127
	v_mov_b32_e32 v78, v127
	v_mov_b32_e32 v77, v127
	v_mov_b32_e32 v76, v127
	v_mov_b32_e32 v75, v127
	v_mov_b32_e32 v74, v127
	v_mov_b32_e32 v73, v127
	v_mov_b32_e32 v72, v127
	v_mov_b32_e32 v119, v127
	v_mov_b32_e32 v118, v127
	v_mov_b32_e32 v117, v127
	v_mov_b32_e32 v116, v127
	v_mov_b32_e32 v115, v127
	v_mov_b32_e32 v114, v127
	v_mov_b32_e32 v113, v127
	v_mov_b32_e32 v112, v127
	v_mov_b32_e32 v103, v127
	v_mov_b32_e32 v102, v127
	v_mov_b32_e32 v101, v127
	v_mov_b32_e32 v100, v127
	v_mov_b32_e32 v99, v127
	v_mov_b32_e32 v98, v127
	v_mov_b32_e32 v97, v127
	v_mov_b32_e32 v96, v127
	v_mov_b32_e32 v87, v127
	v_mov_b32_e32 v86, v127
	v_mov_b32_e32 v85, v127
	v_mov_b32_e32 v84, v127
	v_mov_b32_e32 v83, v127
	v_mov_b32_e32 v82, v127
	v_mov_b32_e32 v81, v127
	v_mov_b32_e32 v80, v127
	v_mov_b32_e32 v71, v127
	v_mov_b32_e32 v70, v127
	v_mov_b32_e32 v69, v127
	v_mov_b32_e32 v68, v127
	v_mov_b32_e32 v67, v127
	v_mov_b32_e32 v66, v127
	v_mov_b32_e32 v65, v127
	v_mov_b32_e32 v64, v127
	v_mov_b32_e32 v63, v127
	v_mov_b32_e32 v62, v127
	v_mov_b32_e32 v61, v127
	v_mov_b32_e32 v60, v127
	v_mov_b32_e32 v59, v127
	v_mov_b32_e32 v58, v127
	v_mov_b32_e32 v57, v127
	v_mov_b32_e32 v56, v127
	v_mov_b32_e32 v47, v127
	v_mov_b32_e32 v46, v127
	v_mov_b32_e32 v45, v127
	v_mov_b32_e32 v44, v127
	v_mov_b32_e32 v43, v127
	v_mov_b32_e32 v42, v127
	v_mov_b32_e32 v41, v127
	v_mov_b32_e32 v40, v127
	v_mov_b32_e32 v31, v127
	v_mov_b32_e32 v30, v127
	v_mov_b32_e32 v29, v127
	v_mov_b32_e32 v28, v127
	v_mov_b32_e32 v27, v127
	v_mov_b32_e32 v26, v127
	v_mov_b32_e32 v25, v127
	v_mov_b32_e32 v24, v127
	v_mov_b32_e32 v15, v127
	v_mov_b32_e32 v14, v127
	v_mov_b32_e32 v13, v127
	v_mov_b32_e32 v12, v127
	v_mov_b32_e32 v11, v127
	v_mov_b32_e32 v10, v127
	v_mov_b32_e32 v9, v127
	v_mov_b32_e32 v8, v127
	v_mov_b32_e32 v55, v127
	v_mov_b32_e32 v54, v127
	v_mov_b32_e32 v53, v127
	v_mov_b32_e32 v52, v127
	v_mov_b32_e32 v51, v127
	v_mov_b32_e32 v50, v127
	v_mov_b32_e32 v49, v127
	v_mov_b32_e32 v48, v127
	v_mov_b32_e32 v39, v127
	v_mov_b32_e32 v38, v127
	v_mov_b32_e32 v37, v127
	v_mov_b32_e32 v36, v127
	v_mov_b32_e32 v35, v127
	v_mov_b32_e32 v34, v127
	v_mov_b32_e32 v33, v127
	v_mov_b32_e32 v32, v127
	v_mov_b32_e32 v23, v127
	v_mov_b32_e32 v22, v127
	v_mov_b32_e32 v21, v127
	v_mov_b32_e32 v20, v127
	v_mov_b32_e32 v19, v127
	v_mov_b32_e32 v18, v127
	v_mov_b32_e32 v17, v127
	v_mov_b32_e32 v16, v127
	v_mov_b32_e32 v7, v127
	v_mov_b32_e32 v6, v127
	v_mov_b32_e32 v5, v127
	v_mov_b32_e32 v4, v127
	v_mov_b32_e32 v3, v127
	v_mov_b32_e32 v2, v127
	s_waitcnt lgkmcnt(0)
	v_mov_b32_e32 v1, v127
	v_mov_b32_e32 v0, v127
	s_cbranch_vccnz .LBB0_767
	s_add_u32 s0, s26, 0x80
	s_addc_u32 s1, s27, 0
	s_add_u32 s60, s24, 0x100
	s_addc_u32 s61, s25, 0
	s_mov_b32 s24, 0
